# first K-loop trip of every GEMM unit peeled: first-touch MFMAs take srcC=0, accumulator zeroing removed
# baseline (speedup 1.0000x reference)
; #define PG8_STAGE(bufoff, gbase, voff) do { _Pragma("unroll") for (int _i = 0; _i < 2; ++_i) \
;         __builtin_amdgcn_global_load_lds((const unsigned*)((const char*)(gbase) + (voff)[_i]), (PG8_LAS unsigned*)(lds + (bufoff) + ldsw + _i * 8192), 16, 0, 0); } while (0)
; #define PG8_LDA(dst, b, h) do { _Pragma("unroll") for (int m = 0; m < 4; ++m) _Pragma("unroll") for (int k = 0; k < 2; ++k) dst[m][k] = *(const PG8_LAS bf16x8*)(lds + PG8_SA(b, h) + aoff + m * 2048 + k * 1024); } while (0)
; #define PG8_LDB(dst, b, h) do { _Pragma("unroll") for (int n = 0; n < 2; ++n) _Pragma("unroll") for (int k = 0; k < 2; ++k) dst[n][k] = *(const PG8_LAS bf16x8*)(lds + PG8_SB(b, h) + boff + n * 2048 + k * 1024); } while (0)
; #define PG8_MMA(ai, bj, At, Bt) do { __builtin_amdgcn_s_setprio(1); _Pragma("unroll") for (int m = 0; m < 4; ++m) _Pragma("unroll") for (int n = 0; n < 2; ++n) _Pragma("unroll") for (int k = 0; k < 2; ++k) \
;         acc[ai][bj][m][n] = __builtin_amdgcn_mfma_f32_16x16x32_bf16(Bt[n][k], At[m][k], acc[ai][bj][m][n], 0, 0, 0); __builtin_amdgcn_s_setprio(0); } while (0)
; #define PG8_WAIT_V(n) asm volatile("s_waitcnt vmcnt(" #n ")" ::: "memory")
; #define PG8_WAIT_L(n) asm volatile("s_waitcnt lgkmcnt(" #n ")" ::: "memory")
; #define PG8_BAR __builtin_amdgcn_s_barrier()
; #define PG8_SCHED __builtin_amdgcn_sched_barrier(0)
; template <class Epi, class Sched, bool ALIGN_EPI = false, bool SP2 = false>
; __device__ __forceinline__ void gemm_phase(PG8_LAS unsigned char* lds, const Gemm g, const Sched& S, const Epi& E) {
;     ...
;             PG8_LDB(B0, 0, 0); PG8_LDB(B1, 0, 1); PG8_SCHED; PG8_LDA(At, 0, 0); PG8_STAGE(PG8_SA(1, 1), a1 + hstep, voffA);
;             PG8_WAIT_V(8); PG8_WAIT_L(0); PG8_BAR; PG8_MMA(0, 0, At, B0); PG8_MMA(0, 1, At, B1); PG8_BAR; PG8_SCHED;
;             PG8_LDA(At, 0, 1); PG8_STAGE(PG8_SB(0, 0), b2, voffB); PG8_STAGE(PG8_SB(0, 1), b2 + hstep, voffB); PG8_STAGE(PG8_SA(0, 0), a2, voffA);
;             PG8_WAIT_V(8); PG8_WAIT_L(0); PG8_BAR; PG8_MMA(1, 0, At, B0); PG8_MMA(1, 1, At, B1); PG8_BAR; PG8_SCHED;
.LBB0_189:
	s_ashr_i32 s75, s74, 31
	s_lshl_b64 s[2:3], s[74:75], 19
	s_add_u32 s80, s64, s2
	s_addc_u32 s81, s65, s3
	s_and_b64 s[2:3], s[0:1], exec
	s_cselect_b32 s2, s81, s7
	s_cselect_b32 s3, s80, s6
	s_ashr_i32 s93, s92, 31
	s_lshl_b64 s[8:9], s[92:93], 19
	s_add_u32 s82, s84, s8
	s_addc_u32 s83, s85, s9
	s_and_b64 s[8:9], s[0:1], exec
	s_cselect_b32 s5, s83, s35
	s_cselect_b32 s8, s82, s34
	s_add_u32 s6, s6, 0x40080
	s_addc_u32 s7, s7, 0
	s_add_u32 s9, s34, 0x100
	s_addc_u32 s33, s35, 0
	s_mov_b32 s46, -2
	s_waitcnt lgkmcnt(0)
	ds_read_b128 v[130:133], v216
	ds_read_b128 v[134:137], v216 offset:1024
	ds_read_b128 v[138:141], v216 offset:2048
	ds_read_b128 v[142:145], v216 offset:3072
	s_waitcnt vmcnt(0)
	ds_read_b128 v[166:169], v217
	ds_read_b128 v[170:173], v217 offset:1024
	ds_read_b128 v[174:177], v217 offset:2048
	ds_read_b128 v[178:181], v217 offset:3072
	s_add_u32 s34, s6, 0xfffc0080
	s_addc_u32 s35, s7, -1
	s_cmp_eq_u32 s46, 12
	s_cselect_b32 s39, s2, s35
	s_cselect_b32 s38, s3, s34
	s_cselect_b32 s35, s5, s33
	s_cselect_b32 s34, s8, s9
	v_lshl_add_u64 v[204:205], s[6:7], 0, v[158:159]
	s_add_i32 m0, s11, 0xc000
	ds_read_b128 v[182:185], v218
	ds_read_b128 v[186:189], v218 offset:1024
	ds_read_b128 v[190:193], v218 offset:2048
	ds_read_b128 v[194:197], v218 offset:3072
	ds_read_b128 v[198:201], v218 offset:4096
	ds_read_b128 v[220:223], v218 offset:5120
	ds_read_b128 v[224:227], v218 offset:6144
	ds_read_b128 v[228:231], v218 offset:7168
	global_load_lds_dwordx4 v[204:205], off
	v_lshl_add_u64 v[204:205], s[6:7], 0, v[160:161]
	s_add_i32 m0, s11, 0xe000
	s_nop 0
	global_load_lds_dwordx4 v[204:205], off
	s_waitcnt vmcnt(8)
	s_waitcnt lgkmcnt(0)
	s_barrier
	s_setprio 1
	s_waitcnt lgkmcnt(0)
	v_mfma_f32_16x16x32_bf16 v[126:129], v[130:133], v[182:185], 0
	v_mfma_f32_16x16x32_bf16 v[122:125], v[138:141], v[182:185], 0
	v_mfma_f32_16x16x32_bf16 v[114:117], v[130:133], v[190:193], 0
	v_mfma_f32_16x16x32_bf16 v[106:109], v[138:141], v[190:193], 0
	v_mfma_f32_16x16x32_bf16 v[98:101], v[130:133], v[198:201], 0
	v_mfma_f32_16x16x32_bf16 v[90:93], v[138:141], v[198:201], 0
	v_mfma_f32_16x16x32_bf16 v[82:85], v[130:133], v[224:227], 0
	v_mfma_f32_16x16x32_bf16 v[74:77], v[138:141], v[224:227], 0
	v_mfma_f32_16x16x32_bf16 v[126:129], v[134:137], v[186:189], v[126:129]
	v_mfma_f32_16x16x32_bf16 v[122:125], v[142:145], v[186:189], v[122:125]
	v_mfma_f32_16x16x32_bf16 v[114:117], v[134:137], v[194:197], v[114:117]
	v_mfma_f32_16x16x32_bf16 v[106:109], v[142:145], v[194:197], v[106:109]
	v_mfma_f32_16x16x32_bf16 v[98:101], v[134:137], v[220:223], v[98:101]
	v_mfma_f32_16x16x32_bf16 v[90:93], v[142:145], v[220:223], v[90:93]
	v_mfma_f32_16x16x32_bf16 v[82:85], v[134:137], v[228:231], v[82:85]
	v_mfma_f32_16x16x32_bf16 v[74:77], v[142:145], v[228:231], v[74:77]
	s_setprio 0
	s_setprio 1
	v_mfma_f32_16x16x32_bf16 v[118:121], v[166:169], v[182:185], 0
	v_mfma_f32_16x16x32_bf16 v[110:113], v[174:177], v[182:185], 0
	v_mfma_f32_16x16x32_bf16 v[102:105], v[166:169], v[190:193], 0
	v_mfma_f32_16x16x32_bf16 v[94:97], v[174:177], v[190:193], 0
	v_mfma_f32_16x16x32_bf16 v[86:89], v[166:169], v[198:201], 0
	v_mfma_f32_16x16x32_bf16 v[78:81], v[174:177], v[198:201], 0
	v_mfma_f32_16x16x32_bf16 v[70:73], v[166:169], v[224:227], 0
	v_mfma_f32_16x16x32_bf16 v[66:69], v[174:177], v[224:227], 0
	v_mfma_f32_16x16x32_bf16 v[118:121], v[170:173], v[186:189], v[118:121]
	v_mfma_f32_16x16x32_bf16 v[110:113], v[178:181], v[186:189], v[110:113]
	v_mfma_f32_16x16x32_bf16 v[102:105], v[170:173], v[194:197], v[102:105]
	v_mfma_f32_16x16x32_bf16 v[94:97], v[178:181], v[194:197], v[94:97]
	v_mfma_f32_16x16x32_bf16 v[86:89], v[170:173], v[220:223], v[86:89]
	v_mfma_f32_16x16x32_bf16 v[78:81], v[178:181], v[220:223], v[78:81]
	v_mfma_f32_16x16x32_bf16 v[70:73], v[170:173], v[228:231], v[70:73]
	v_mfma_f32_16x16x32_bf16 v[66:69], v[178:181], v[228:231], v[66:69]
	s_setprio 0
	s_barrier
	s_add_i32 s47, s44, s10
	v_lshl_add_u64 v[204:205], s[34:35], 0, v[148:149]
	s_mov_b32 m0, s47
	ds_read_b128 v[182:185], v218 offset:16384
	ds_read_b128 v[186:189], v218 offset:17408
	ds_read_b128 v[190:193], v218 offset:18432
	ds_read_b128 v[194:197], v218 offset:19456
	ds_read_b128 v[198:201], v218 offset:20480
	ds_read_b128 v[220:223], v218 offset:21504
	ds_read_b128 v[224:227], v218 offset:22528
	ds_read_b128 v[228:231], v218 offset:23552
	global_load_lds_dwordx4 v[204:205], off
	s_add_i32 m0, s47, 0x2000
	s_add_u32 s48, s34, 0x40000
	v_lshl_add_u64 v[232:233], s[34:35], 0, v[152:153]
	s_addc_u32 s49, s35, 0
	s_add_i32 s47, s45, s10
	global_load_lds_dwordx4 v[232:233], off
	v_lshl_add_u64 v[234:235], s[48:49], 0, v[148:149]
	s_mov_b32 m0, s47
	v_lshl_add_u64 v[236:237], s[38:39], 0, v[150:151]
	global_load_lds_dwordx4 v[234:235], off
	v_lshl_add_u64 v[234:235], s[48:49], 0, v[152:153]
	s_add_i32 m0, s47, 0x2000
	s_nop 0
	global_load_lds_dwordx4 v[234:235], off
	v_lshl_add_u64 v[234:235], s[38:39], 0, v[146:147]
	s_mov_b32 m0, s11
	s_nop 0
	global_load_lds_dwordx4 v[234:235], off
	s_mov_b32 m0, s25
	s_nop 0
	global_load_lds_dwordx4 v[236:237], off
	s_waitcnt vmcnt(8)
	s_waitcnt lgkmcnt(0)
	s_barrier
; #define PG8_STAGE(bufoff, gbase, voff) do { _Pragma("unroll") for (int _i = 0; _i < 2; ++_i) \
;         __builtin_amdgcn_global_load_lds((const unsigned*)((const char*)(gbase) + (voff)[_i]), (PG8_LAS unsigned*)(lds + (bufoff) + ldsw + _i * 8192), 16, 0, 0); } while (0)
; #define PG8_LDA(dst, b, h) do { _Pragma("unroll") for (int m = 0; m < 4; ++m) _Pragma("unroll") for (int k = 0; k < 2; ++k) dst[m][k] = *(const PG8_LAS bf16x8*)(lds + PG8_SA(b, h) + aoff + m * 2048 + k * 1024); } while (0)
; #define PG8_LDB(dst, b, h) do { _Pragma("unroll") for (int n = 0; n < 2; ++n) _Pragma("unroll") for (int k = 0; k < 2; ++k) dst[n][k] = *(const PG8_LAS bf16x8*)(lds + PG8_SB(b, h) + boff + n * 2048 + k * 1024); } while (0)
; #define PG8_MMA(ai, bj, At, Bt) do { __builtin_amdgcn_s_setprio(1); _Pragma("unroll") for (int m = 0; m < 4; ++m) _Pragma("unroll") for (int n = 0; n < 2; ++n) _Pragma("unroll") for (int k = 0; k < 2; ++k) \
;         acc[ai][bj][m][n] = __builtin_amdgcn_mfma_f32_16x16x32_bf16(Bt[n][k], At[m][k], acc[ai][bj][m][n], 0, 0, 0); __builtin_amdgcn_s_setprio(0); } while (0)
; #define PG8_WAIT_V(n) asm volatile("s_waitcnt vmcnt(" #n ")" ::: "memory")
; #define PG8_WAIT_L(n) asm volatile("s_waitcnt lgkmcnt(" #n ")" ::: "memory")
; #define PG8_BAR __builtin_amdgcn_s_barrier()
; #define PG8_SCHED __builtin_amdgcn_sched_barrier(0)
; template <class Epi, class Sched, bool ALIGN_EPI = false, bool SP2 = false>
; __device__ __forceinline__ void gemm_phase(PG8_LAS unsigned char* lds, const Gemm g, const Sched& S, const Epi& E) {
;     ...
;             PG8_WAIT_V(8); PG8_WAIT_L(0); PG8_BAR; PG8_MMA(1, 0, At, B0); PG8_MMA(1, 1, At, B1); PG8_BAR; PG8_SCHED;
;             PG8_LDB(B0, 1, 0); PG8_LDB(B1, 1, 1); PG8_SCHED; PG8_LDA(At, 1, 0); PG8_STAGE(PG8_SA(0, 1), a2 + hstep, voffA);
;             PG8_WAIT_V(8); PG8_WAIT_L(0); PG8_BAR; PG8_MMA(0, 0, At, B0); PG8_MMA(0, 1, At, B1); PG8_BAR; PG8_SCHED;
	s_setprio 1
	s_waitcnt lgkmcnt(0)
	v_mfma_f32_16x16x32_bf16 v[62:65], v[130:133], v[182:185], 0
	v_mfma_f32_16x16x32_bf16 v[58:61], v[138:141], v[182:185], 0
	v_mfma_f32_16x16x32_bf16 v[50:53], v[130:133], v[190:193], 0
	v_mfma_f32_16x16x32_bf16 v[42:45], v[138:141], v[190:193], 0
	v_mfma_f32_16x16x32_bf16 v[34:37], v[130:133], v[198:201], 0
	v_mfma_f32_16x16x32_bf16 v[26:29], v[138:141], v[198:201], 0
	v_mfma_f32_16x16x32_bf16 v[18:21], v[130:133], v[224:227], 0
	v_mfma_f32_16x16x32_bf16 v[10:13], v[138:141], v[224:227], 0
	v_mfma_f32_16x16x32_bf16 v[62:65], v[134:137], v[186:189], v[62:65]
	v_mfma_f32_16x16x32_bf16 v[58:61], v[142:145], v[186:189], v[58:61]
	v_mfma_f32_16x16x32_bf16 v[50:53], v[134:137], v[194:197], v[50:53]
	v_mfma_f32_16x16x32_bf16 v[42:45], v[142:145], v[194:197], v[42:45]
	v_mfma_f32_16x16x32_bf16 v[34:37], v[134:137], v[220:223], v[34:37]
	v_mfma_f32_16x16x32_bf16 v[26:29], v[142:145], v[220:223], v[26:29]
	v_mfma_f32_16x16x32_bf16 v[18:21], v[134:137], v[228:231], v[18:21]
	v_mfma_f32_16x16x32_bf16 v[10:13], v[142:145], v[228:231], v[10:13]
	s_setprio 0
	s_setprio 1
	v_mfma_f32_16x16x32_bf16 v[54:57], v[166:169], v[182:185], 0
	v_mfma_f32_16x16x32_bf16 v[46:49], v[174:177], v[182:185], 0
	v_mfma_f32_16x16x32_bf16 v[38:41], v[166:169], v[190:193], 0
	v_mfma_f32_16x16x32_bf16 v[30:33], v[174:177], v[190:193], 0
	v_mfma_f32_16x16x32_bf16 v[22:25], v[166:169], v[198:201], 0
	v_mfma_f32_16x16x32_bf16 v[14:17], v[174:177], v[198:201], 0
	v_mfma_f32_16x16x32_bf16 v[6:9], v[166:169], v[224:227], 0
	v_mfma_f32_16x16x32_bf16 v[2:5], v[174:177], v[224:227], 0
	v_mfma_f32_16x16x32_bf16 v[54:57], v[170:173], v[186:189], v[54:57]
	v_mfma_f32_16x16x32_bf16 v[46:49], v[178:181], v[186:189], v[46:49]
	v_mfma_f32_16x16x32_bf16 v[38:41], v[170:173], v[194:197], v[38:41]
	v_mfma_f32_16x16x32_bf16 v[30:33], v[178:181], v[194:197], v[30:33]
	v_mfma_f32_16x16x32_bf16 v[22:25], v[170:173], v[220:223], v[22:25]
	v_mfma_f32_16x16x32_bf16 v[14:17], v[178:181], v[220:223], v[14:17]
	v_mfma_f32_16x16x32_bf16 v[6:9], v[170:173], v[228:231], v[6:9]
	v_mfma_f32_16x16x32_bf16 v[2:5], v[178:181], v[228:231], v[2:5]
	s_setprio 0
	s_barrier
	s_add_i32 s47, 0, 0x18000
	s_add_i32 s48, 0, 0x1c000
	v_add_u32_e32 v142, s47, v214
	v_add_u32_e32 v178, s48, v214
	ds_read_b128 v[130:133], v142
	ds_read_b128 v[134:137], v142 offset:1024
	ds_read_b128 v[138:141], v142 offset:2048
	ds_read_b128 v[142:145], v142 offset:3072
	ds_read_b128 v[166:169], v178
	ds_read_b128 v[170:173], v178 offset:1024
	ds_read_b128 v[174:177], v178 offset:2048
	ds_read_b128 v[178:181], v178 offset:3072
	s_add_u32 s38, s38, 0x40000
	s_addc_u32 s39, s39, 0
	s_mov_b32 m0, s27
	v_lshl_add_u64 v[238:239], s[38:39], 0, v[146:147]
	ds_read_b128 v[182:185], v218 offset:32768
	ds_read_b128 v[186:189], v218 offset:33792
	ds_read_b128 v[190:193], v218 offset:34816
	ds_read_b128 v[194:197], v218 offset:35840
	ds_read_b128 v[198:201], v218 offset:36864
	ds_read_b128 v[220:223], v218 offset:37888
	ds_read_b128 v[224:227], v218 offset:38912
	ds_read_b128 v[228:231], v218 offset:39936
	global_load_lds_dwordx4 v[238:239], off
	v_lshl_add_u64 v[238:239], s[38:39], 0, v[150:151]
	s_mov_b32 m0, s29
	s_nop 0
	global_load_lds_dwordx4 v[238:239], off
	s_waitcnt vmcnt(8)
	s_waitcnt lgkmcnt(0)
	s_barrier
	s_setprio 1
	s_waitcnt lgkmcnt(0)
	v_mfma_f32_16x16x32_bf16 v[126:129], v[130:133], v[182:185], v[126:129]
	v_mfma_f32_16x16x32_bf16 v[122:125], v[138:141], v[182:185], v[122:125]
	v_mfma_f32_16x16x32_bf16 v[114:117], v[130:133], v[190:193], v[114:117]
	v_mfma_f32_16x16x32_bf16 v[106:109], v[138:141], v[190:193], v[106:109]
	v_mfma_f32_16x16x32_bf16 v[98:101], v[130:133], v[198:201], v[98:101]
	v_mfma_f32_16x16x32_bf16 v[90:93], v[138:141], v[198:201], v[90:93]
	v_mfma_f32_16x16x32_bf16 v[82:85], v[130:133], v[224:227], v[82:85]
	v_mfma_f32_16x16x32_bf16 v[74:77], v[138:141], v[224:227], v[74:77]
	v_mfma_f32_16x16x32_bf16 v[126:129], v[134:137], v[186:189], v[126:129]
	v_mfma_f32_16x16x32_bf16 v[122:125], v[142:145], v[186:189], v[122:125]
	v_mfma_f32_16x16x32_bf16 v[114:117], v[134:137], v[194:197], v[114:117]
	v_mfma_f32_16x16x32_bf16 v[106:109], v[142:145], v[194:197], v[106:109]
	v_mfma_f32_16x16x32_bf16 v[98:101], v[134:137], v[220:223], v[98:101]
	v_mfma_f32_16x16x32_bf16 v[90:93], v[142:145], v[220:223], v[90:93]
	v_mfma_f32_16x16x32_bf16 v[82:85], v[134:137], v[228:231], v[82:85]
	v_mfma_f32_16x16x32_bf16 v[74:77], v[142:145], v[228:231], v[74:77]
	s_setprio 0
	s_setprio 1
	v_mfma_f32_16x16x32_bf16 v[118:121], v[166:169], v[182:185], v[118:121]
	v_mfma_f32_16x16x32_bf16 v[110:113], v[174:177], v[182:185], v[110:113]
	v_mfma_f32_16x16x32_bf16 v[102:105], v[166:169], v[190:193], v[102:105]
	v_mfma_f32_16x16x32_bf16 v[94:97], v[174:177], v[190:193], v[94:97]
	v_mfma_f32_16x16x32_bf16 v[86:89], v[166:169], v[198:201], v[86:89]
	v_mfma_f32_16x16x32_bf16 v[78:81], v[174:177], v[198:201], v[78:81]
	v_mfma_f32_16x16x32_bf16 v[70:73], v[166:169], v[224:227], v[70:73]
	v_mfma_f32_16x16x32_bf16 v[66:69], v[174:177], v[224:227], v[66:69]
	v_mfma_f32_16x16x32_bf16 v[118:121], v[170:173], v[186:189], v[118:121]
	v_mfma_f32_16x16x32_bf16 v[110:113], v[178:181], v[186:189], v[110:113]
	v_mfma_f32_16x16x32_bf16 v[102:105], v[170:173], v[194:197], v[102:105]
	v_mfma_f32_16x16x32_bf16 v[94:97], v[178:181], v[194:197], v[94:97]
	v_mfma_f32_16x16x32_bf16 v[86:89], v[170:173], v[220:223], v[86:89]
	v_mfma_f32_16x16x32_bf16 v[78:81], v[178:181], v[220:223], v[78:81]
	v_mfma_f32_16x16x32_bf16 v[70:73], v[170:173], v[228:231], v[70:73]
	v_mfma_f32_16x16x32_bf16 v[66:69], v[178:181], v[228:231], v[66:69]
	s_setprio 0
	s_barrier
; #define PG8_STAGE(bufoff, gbase, voff) do { _Pragma("unroll") for (int _i = 0; _i < 2; ++_i) \
;         __builtin_amdgcn_global_load_lds((const unsigned*)((const char*)(gbase) + (voff)[_i]), (PG8_LAS unsigned*)(lds + (bufoff) + ldsw + _i * 8192), 16, 0, 0); } while (0)
; #define PG8_LDA(dst, b, h) do { _Pragma("unroll") for (int m = 0; m < 4; ++m) _Pragma("unroll") for (int k = 0; k < 2; ++k) dst[m][k] = *(const PG8_LAS bf16x8*)(lds + PG8_SA(b, h) + aoff + m * 2048 + k * 1024); } while (0)
; #define PG8_MMA(ai, bj, At, Bt) do { __builtin_amdgcn_s_setprio(1); _Pragma("unroll") for (int m = 0; m < 4; ++m) _Pragma("unroll") for (int n = 0; n < 2; ++n) _Pragma("unroll") for (int k = 0; k < 2; ++k) \
;         acc[ai][bj][m][n] = __builtin_amdgcn_mfma_f32_16x16x32_bf16(Bt[n][k], At[m][k], acc[ai][bj][m][n], 0, 0, 0); __builtin_amdgcn_s_setprio(0); } while (0)
; #define PG8_WAIT_V(n) asm volatile("s_waitcnt vmcnt(" #n ")" ::: "memory")
; #define PG8_WAIT_L(n) asm volatile("s_waitcnt lgkmcnt(" #n ")" ::: "memory")
; #define PG8_BAR __builtin_amdgcn_s_barrier()
; #define PG8_SCHED __builtin_amdgcn_sched_barrier(0)
; template <class Epi, class Sched, bool ALIGN_EPI = false, bool SP2 = false>
; __device__ __forceinline__ void gemm_phase(PG8_LAS unsigned char* lds, const Gemm g, const Sched& S, const Epi& E) {
;     ...
;             PG8_LDA(At, 1, 1); PG8_STAGE(PG8_SB(1, 0), b3, voffB); PG8_STAGE(PG8_SB(1, 1), b3 + hstep, voffB); PG8_STAGE(PG8_SA(1, 0), a3, voffA);
;             PG8_WAIT_V(8); PG8_WAIT_L(0); PG8_BAR; PG8_MMA(1, 0, At, B0); PG8_MMA(1, 1, At, B1); PG8_BAR; PG8_SCHED;
	s_add_i32 s38, s47, s10
	v_lshl_add_u64 v[204:205], v[204:205], 0, s[20:21]
	s_mov_b32 m0, s38
	ds_read_b128 v[182:185], v218 offset:49152
	ds_read_b128 v[186:189], v218 offset:50176
	ds_read_b128 v[190:193], v218 offset:51200
	ds_read_b128 v[194:197], v218 offset:52224
	ds_read_b128 v[198:201], v218 offset:53248
	ds_read_b128 v[220:223], v218 offset:54272
	ds_read_b128 v[224:227], v218 offset:55296
	ds_read_b128 v[228:231], v218 offset:56320
	global_load_lds_dwordx4 v[204:205], off
	s_add_i32 m0, s38, 0x2000
	s_add_u32 s34, s34, 0x40080
	v_lshl_add_u64 v[204:205], v[232:233], 0, s[20:21]
	s_addc_u32 s35, s35, 0
	s_add_i32 s38, s48, s10
	global_load_lds_dwordx4 v[204:205], off
	v_lshl_add_u64 v[204:205], s[34:35], 0, v[148:149]
	s_mov_b32 m0, s38
	s_nop 0
	global_load_lds_dwordx4 v[204:205], off
	v_lshl_add_u64 v[204:205], s[34:35], 0, v[152:153]
	s_add_i32 m0, s38, 0x2000
	s_nop 0
	global_load_lds_dwordx4 v[204:205], off
	v_lshl_add_u64 v[204:205], v[234:235], 0, s[20:21]
	s_mov_b32 m0, s40
	s_nop 0
	global_load_lds_dwordx4 v[204:205], off
	v_lshl_add_u64 v[204:205], v[236:237], 0, s[20:21]
	s_mov_b32 m0, s41
	s_nop 0
	global_load_lds_dwordx4 v[204:205], off
	s_waitcnt vmcnt(8)
	s_waitcnt lgkmcnt(0)
	s_barrier
	s_setprio 1
	s_waitcnt lgkmcnt(0)
	v_mfma_f32_16x16x32_bf16 v[62:65], v[130:133], v[182:185], v[62:65]
	v_mfma_f32_16x16x32_bf16 v[58:61], v[138:141], v[182:185], v[58:61]
	v_mfma_f32_16x16x32_bf16 v[50:53], v[130:133], v[190:193], v[50:53]
	v_mfma_f32_16x16x32_bf16 v[42:45], v[138:141], v[190:193], v[42:45]
	v_mfma_f32_16x16x32_bf16 v[34:37], v[130:133], v[198:201], v[34:37]
	v_mfma_f32_16x16x32_bf16 v[26:29], v[138:141], v[198:201], v[26:29]
	v_mfma_f32_16x16x32_bf16 v[18:21], v[130:133], v[224:227], v[18:21]
	v_mfma_f32_16x16x32_bf16 v[10:13], v[138:141], v[224:227], v[10:13]
	v_mfma_f32_16x16x32_bf16 v[62:65], v[134:137], v[186:189], v[62:65]
	v_mfma_f32_16x16x32_bf16 v[58:61], v[142:145], v[186:189], v[58:61]
	v_mfma_f32_16x16x32_bf16 v[50:53], v[134:137], v[194:197], v[50:53]
	v_mfma_f32_16x16x32_bf16 v[42:45], v[142:145], v[194:197], v[42:45]
	v_mfma_f32_16x16x32_bf16 v[34:37], v[134:137], v[220:223], v[34:37]
	v_mfma_f32_16x16x32_bf16 v[26:29], v[142:145], v[220:223], v[26:29]
	v_mfma_f32_16x16x32_bf16 v[18:21], v[134:137], v[228:231], v[18:21]
	v_mfma_f32_16x16x32_bf16 v[10:13], v[142:145], v[228:231], v[10:13]
	s_setprio 0
	s_setprio 1
	v_mfma_f32_16x16x32_bf16 v[54:57], v[166:169], v[182:185], v[54:57]
	v_mfma_f32_16x16x32_bf16 v[46:49], v[174:177], v[182:185], v[46:49]
	v_mfma_f32_16x16x32_bf16 v[38:41], v[166:169], v[190:193], v[38:41]
	v_mfma_f32_16x16x32_bf16 v[30:33], v[174:177], v[190:193], v[30:33]
	v_mfma_f32_16x16x32_bf16 v[22:25], v[166:169], v[198:201], v[22:25]
	v_mfma_f32_16x16x32_bf16 v[14:17], v[174:177], v[198:201], v[14:17]
	v_mfma_f32_16x16x32_bf16 v[6:9], v[166:169], v[224:227], v[6:9]
	v_mfma_f32_16x16x32_bf16 v[2:5], v[174:177], v[224:227], v[2:5]
	v_mfma_f32_16x16x32_bf16 v[54:57], v[170:173], v[186:189], v[54:57]
	v_mfma_f32_16x16x32_bf16 v[46:49], v[178:181], v[186:189], v[46:49]
	v_mfma_f32_16x16x32_bf16 v[38:41], v[170:173], v[194:197], v[38:41]
	v_mfma_f32_16x16x32_bf16 v[30:33], v[178:181], v[194:197], v[30:33]
	v_mfma_f32_16x16x32_bf16 v[22:25], v[170:173], v[220:223], v[22:25]
	v_mfma_f32_16x16x32_bf16 v[14:17], v[178:181], v[220:223], v[14:17]
	v_mfma_f32_16x16x32_bf16 v[6:9], v[170:173], v[228:231], v[6:9]
	v_mfma_f32_16x16x32_bf16 v[2:5], v[178:181], v[228:231], v[2:5]
	s_setprio 0
	s_barrier
	s_add_i32 s46, s46, 2
	s_add_u32 s6, s6, 0x100
	s_addc_u32 s7, s7, 0
	s_add_u32 s9, s9, 0x100
	s_addc_u32 s33, s33, 0
	s_cmp_gt_u32 s46, 13
	s_cbranch_scc0 .LBB0_190
	s_branch .Lkexit0

; #define PG8_BAR __builtin_amdgcn_s_barrier()
; template <class Epi, class Sched, bool ALIGN_EPI = false, bool SP2 = false>
; __device__ __forceinline__ void gemm_phase(PG8_LAS unsigned char* lds, const Gemm g, const Sched& S, const Epi& E) {
;     ...
;         if constexpr (ALIGN_EPI) { if (wr == 0) PG8_BAR; }
;         if constexpr (!Epi::AFTER_DRAIN) { E(acc, cur, wr, wc, fr, fq); S.done(cur); }
.Lkexit0:
	s_and_b64 vcc, exec, s[22:23]
	s_cbranch_vccz .LBB0_193
	s_barrier

; #define PG8_STAGE(bufoff, gbase, voff) do { _Pragma("unroll") for (int _i = 0; _i < 2; ++_i) \
;         __builtin_amdgcn_global_load_lds((const unsigned*)((const char*)(gbase) + (voff)[_i]), (PG8_LAS unsigned*)(lds + (bufoff) + ldsw + _i * 8192), 16, 0, 0); } while (0)
; #define PG8_LDA(dst, b, h) do { _Pragma("unroll") for (int m = 0; m < 4; ++m) _Pragma("unroll") for (int k = 0; k < 2; ++k) dst[m][k] = *(const PG8_LAS bf16x8*)(lds + PG8_SA(b, h) + aoff + m * 2048 + k * 1024); } while (0)
; #define PG8_LDB(dst, b, h) do { _Pragma("unroll") for (int n = 0; n < 2; ++n) _Pragma("unroll") for (int k = 0; k < 2; ++k) dst[n][k] = *(const PG8_LAS bf16x8*)(lds + PG8_SB(b, h) + boff + n * 2048 + k * 1024); } while (0)
; #define PG8_MMA(ai, bj, At, Bt) do { __builtin_amdgcn_s_setprio(1); _Pragma("unroll") for (int m = 0; m < 4; ++m) _Pragma("unroll") for (int n = 0; n < 2; ++n) _Pragma("unroll") for (int k = 0; k < 2; ++k) \
;         acc[ai][bj][m][n] = __builtin_amdgcn_mfma_f32_16x16x32_bf16(Bt[n][k], At[m][k], acc[ai][bj][m][n], 0, 0, 0); __builtin_amdgcn_s_setprio(0); } while (0)
; #define PG8_WAIT_V(n) asm volatile("s_waitcnt vmcnt(" #n ")" ::: "memory")
; #define PG8_WAIT_L(n) asm volatile("s_waitcnt lgkmcnt(" #n ")" ::: "memory")
; #define PG8_BAR __builtin_amdgcn_s_barrier()
; #define PG8_SCHED __builtin_amdgcn_sched_barrier(0)
; template <class Epi, class Sched, bool ALIGN_EPI = false, bool SP2 = false>
; __device__ __forceinline__ void gemm_phase(PG8_LAS unsigned char* lds, const Gemm g, const Sched& S, const Epi& E) {
;     ...
;             PG8_LDB(B0, 0, 0); PG8_LDB(B1, 0, 1); PG8_SCHED; PG8_LDA(At, 0, 0); PG8_STAGE(PG8_SA(1, 1), a1 + hstep, voffA);
;             PG8_WAIT_V(8); PG8_WAIT_L(0); PG8_BAR; PG8_MMA(0, 0, At, B0); PG8_MMA(0, 1, At, B1); PG8_BAR; PG8_SCHED;
;             PG8_LDA(At, 0, 1); PG8_STAGE(PG8_SB(0, 0), b2, voffB); PG8_STAGE(PG8_SB(0, 1), b2 + hstep, voffB); PG8_STAGE(PG8_SA(0, 0), a2, voffA);
;             PG8_WAIT_V(8); PG8_WAIT_L(0); PG8_BAR; PG8_MMA(1, 0, At, B0); PG8_MMA(1, 1, At, B1); PG8_BAR; PG8_SCHED;
.LBB0_327:
	s_ashr_i32 s21, s20, 31
	s_lshl_b64 s[2:3], s[20:21], 19
	s_add_u32 s22, s55, s2
	s_addc_u32 s23, s56, s3
	s_and_b64 s[2:3], s[12:13], exec
	s_cselect_b32 s2, s23, s27
	s_cselect_b32 s3, s22, s26
	s_ashr_i32 s19, s18, 31
	s_lshl_b64 s[24:25], s[18:19], 19
	s_add_u32 s24, s74, s24
	s_addc_u32 s25, s75, s25
	s_and_b64 s[30:31], s[12:13], exec
	s_cselect_b32 s19, s25, s29
	s_cselect_b32 s21, s24, s28
	s_add_u32 s26, s26, 0x40080
	s_addc_u32 s27, s27, 0
	s_add_u32 s47, s28, 0x100
	s_addc_u32 s48, s29, 0
	s_mov_b32 s49, -2
	s_waitcnt lgkmcnt(0)
	ds_read_b128 v[138:141], v144
	ds_read_b128 v[156:159], v144 offset:1024
	ds_read_b128 v[160:163], v144 offset:2048
	ds_read_b128 v[164:167], v144 offset:3072
	ds_read_b128 v[168:171], v145
	ds_read_b128 v[172:175], v145 offset:1024
	ds_read_b128 v[176:179], v145 offset:2048
	ds_read_b128 v[180:183], v145 offset:3072
	s_add_u32 s28, s26, 0xfffc0080
	s_addc_u32 s29, s27, -1
	s_cmp_eq_u32 s49, 12
	s_cselect_b32 s31, s2, s29
	s_cselect_b32 s30, s3, s28
	s_cselect_b32 s29, s19, s48
	s_cselect_b32 s28, s21, s47
	v_lshl_add_u64 v[200:201], s[26:27], 0, v[134:135]
	s_add_i32 m0, s34, 0xc000
	ds_read_b128 v[184:187], v154
	ds_read_b128 v[188:191], v154 offset:1024
	ds_read_b128 v[192:195], v154 offset:2048
	ds_read_b128 v[196:199], v154 offset:3072
	ds_read_b128 v[204:207], v154 offset:4096
	ds_read_b128 v[208:211], v154 offset:5120
	ds_read_b128 v[212:215], v154 offset:6144
	ds_read_b128 v[216:219], v154 offset:7168
	global_load_lds_dwordx4 v[200:201], off
	v_lshl_add_u64 v[200:201], s[26:27], 0, v[136:137]
	s_add_i32 m0, s34, 0xe000
	s_nop 0
	global_load_lds_dwordx4 v[200:201], off
	s_waitcnt vmcnt(8)
	s_waitcnt lgkmcnt(0)
	s_barrier
	s_setprio 1
	s_waitcnt lgkmcnt(0)
	v_mfma_f32_16x16x32_bf16 v[126:129], v[138:141], v[184:187], 0
	v_mfma_f32_16x16x32_bf16 v[122:125], v[160:163], v[184:187], 0
	v_mfma_f32_16x16x32_bf16 v[114:117], v[138:141], v[192:195], 0
	v_mfma_f32_16x16x32_bf16 v[106:109], v[160:163], v[192:195], 0
	v_mfma_f32_16x16x32_bf16 v[98:101], v[138:141], v[204:207], 0
	v_mfma_f32_16x16x32_bf16 v[90:93], v[160:163], v[204:207], 0
	v_mfma_f32_16x16x32_bf16 v[82:85], v[138:141], v[212:215], 0
	v_mfma_f32_16x16x32_bf16 v[74:77], v[160:163], v[212:215], 0
	v_mfma_f32_16x16x32_bf16 v[126:129], v[156:159], v[188:191], v[126:129]
	v_mfma_f32_16x16x32_bf16 v[122:125], v[164:167], v[188:191], v[122:125]
	v_mfma_f32_16x16x32_bf16 v[114:117], v[156:159], v[196:199], v[114:117]
	v_mfma_f32_16x16x32_bf16 v[106:109], v[164:167], v[196:199], v[106:109]
	v_mfma_f32_16x16x32_bf16 v[98:101], v[156:159], v[208:211], v[98:101]
	v_mfma_f32_16x16x32_bf16 v[90:93], v[164:167], v[208:211], v[90:93]
	v_mfma_f32_16x16x32_bf16 v[82:85], v[156:159], v[216:219], v[82:85]
	v_mfma_f32_16x16x32_bf16 v[74:77], v[164:167], v[216:219], v[74:77]
	s_setprio 0
	s_setprio 1
	v_mfma_f32_16x16x32_bf16 v[118:121], v[168:171], v[184:187], 0
	v_mfma_f32_16x16x32_bf16 v[110:113], v[176:179], v[184:187], 0
	v_mfma_f32_16x16x32_bf16 v[102:105], v[168:171], v[192:195], 0
	v_mfma_f32_16x16x32_bf16 v[94:97], v[176:179], v[192:195], 0
	v_mfma_f32_16x16x32_bf16 v[86:89], v[168:171], v[204:207], 0
	v_mfma_f32_16x16x32_bf16 v[78:81], v[176:179], v[204:207], 0
	v_mfma_f32_16x16x32_bf16 v[70:73], v[168:171], v[212:215], 0
	v_mfma_f32_16x16x32_bf16 v[66:69], v[176:179], v[212:215], 0
	v_mfma_f32_16x16x32_bf16 v[118:121], v[172:175], v[188:191], v[118:121]
	v_mfma_f32_16x16x32_bf16 v[110:113], v[180:183], v[188:191], v[110:113]
	v_mfma_f32_16x16x32_bf16 v[102:105], v[172:175], v[196:199], v[102:105]
	v_mfma_f32_16x16x32_bf16 v[94:97], v[180:183], v[196:199], v[94:97]
	v_mfma_f32_16x16x32_bf16 v[86:89], v[172:175], v[208:211], v[86:89]
	v_mfma_f32_16x16x32_bf16 v[78:81], v[180:183], v[208:211], v[78:81]
	v_mfma_f32_16x16x32_bf16 v[70:73], v[172:175], v[216:219], v[70:73]
	v_mfma_f32_16x16x32_bf16 v[66:69], v[180:183], v[216:219], v[66:69]
	s_setprio 0
	s_barrier
	s_add_i32 s50, s43, s33
	v_lshl_add_u64 v[200:201], s[28:29], 0, v[148:149]
	s_mov_b32 m0, s50
	ds_read_b128 v[184:187], v154 offset:16384
	ds_read_b128 v[188:191], v154 offset:17408
	ds_read_b128 v[192:195], v154 offset:18432
	ds_read_b128 v[196:199], v154 offset:19456
	ds_read_b128 v[204:207], v154 offset:20480
	ds_read_b128 v[208:211], v154 offset:21504
	ds_read_b128 v[212:215], v154 offset:22528
	ds_read_b128 v[216:219], v154 offset:23552
	global_load_lds_dwordx4 v[200:201], off
	s_add_i32 m0, s50, 0x2000
	s_add_u32 s50, s28, 0x40000
	v_lshl_add_u64 v[220:221], s[28:29], 0, v[152:153]
	s_addc_u32 s51, s29, 0
	s_add_i32 s54, s44, s33
	global_load_lds_dwordx4 v[220:221], off
	v_lshl_add_u64 v[222:223], s[50:51], 0, v[148:149]
	s_mov_b32 m0, s54
	v_lshl_add_u64 v[224:225], s[30:31], 0, v[150:151]
	global_load_lds_dwordx4 v[222:223], off
	v_lshl_add_u64 v[222:223], s[50:51], 0, v[152:153]
	s_add_i32 m0, s54, 0x2000
	s_nop 0
	global_load_lds_dwordx4 v[222:223], off
	v_lshl_add_u64 v[222:223], s[30:31], 0, v[146:147]
	s_mov_b32 m0, s34
	s_nop 0
	global_load_lds_dwordx4 v[222:223], off
	s_mov_b32 m0, s35
	s_nop 0
	global_load_lds_dwordx4 v[224:225], off
	s_waitcnt vmcnt(8)
	s_waitcnt lgkmcnt(0)
	s_barrier
; #define PG8_STAGE(bufoff, gbase, voff) do { _Pragma("unroll") for (int _i = 0; _i < 2; ++_i) \
;         __builtin_amdgcn_global_load_lds((const unsigned*)((const char*)(gbase) + (voff)[_i]), (PG8_LAS unsigned*)(lds + (bufoff) + ldsw + _i * 8192), 16, 0, 0); } while (0)
; #define PG8_LDA(dst, b, h) do { _Pragma("unroll") for (int m = 0; m < 4; ++m) _Pragma("unroll") for (int k = 0; k < 2; ++k) dst[m][k] = *(const PG8_LAS bf16x8*)(lds + PG8_SA(b, h) + aoff + m * 2048 + k * 1024); } while (0)
; #define PG8_LDB(dst, b, h) do { _Pragma("unroll") for (int n = 0; n < 2; ++n) _Pragma("unroll") for (int k = 0; k < 2; ++k) dst[n][k] = *(const PG8_LAS bf16x8*)(lds + PG8_SB(b, h) + boff + n * 2048 + k * 1024); } while (0)
; #define PG8_MMA(ai, bj, At, Bt) do { __builtin_amdgcn_s_setprio(1); _Pragma("unroll") for (int m = 0; m < 4; ++m) _Pragma("unroll") for (int n = 0; n < 2; ++n) _Pragma("unroll") for (int k = 0; k < 2; ++k) \
;         acc[ai][bj][m][n] = __builtin_amdgcn_mfma_f32_16x16x32_bf16(Bt[n][k], At[m][k], acc[ai][bj][m][n], 0, 0, 0); __builtin_amdgcn_s_setprio(0); } while (0)
; #define PG8_WAIT_V(n) asm volatile("s_waitcnt vmcnt(" #n ")" ::: "memory")
; #define PG8_WAIT_L(n) asm volatile("s_waitcnt lgkmcnt(" #n ")" ::: "memory")
; #define PG8_BAR __builtin_amdgcn_s_barrier()
; #define PG8_SCHED __builtin_amdgcn_sched_barrier(0)
; template <class Epi, class Sched, bool ALIGN_EPI = false, bool SP2 = false>
; __device__ __forceinline__ void gemm_phase(PG8_LAS unsigned char* lds, const Gemm g, const Sched& S, const Epi& E) {
;     ...
;             PG8_WAIT_V(8); PG8_WAIT_L(0); PG8_BAR; PG8_MMA(1, 0, At, B0); PG8_MMA(1, 1, At, B1); PG8_BAR; PG8_SCHED;
;             PG8_LDB(B0, 1, 0); PG8_LDB(B1, 1, 1); PG8_SCHED; PG8_LDA(At, 1, 0); PG8_STAGE(PG8_SA(0, 1), a2 + hstep, voffA);
;             PG8_WAIT_V(8); PG8_WAIT_L(0); PG8_BAR; PG8_MMA(0, 0, At, B0); PG8_MMA(0, 1, At, B1); PG8_BAR; PG8_SCHED;
	s_setprio 1
	s_waitcnt lgkmcnt(0)
	v_mfma_f32_16x16x32_bf16 v[62:65], v[138:141], v[184:187], 0
	v_mfma_f32_16x16x32_bf16 v[58:61], v[160:163], v[184:187], 0
	v_mfma_f32_16x16x32_bf16 v[54:57], v[138:141], v[192:195], 0
	v_mfma_f32_16x16x32_bf16 v[46:49], v[160:163], v[192:195], 0
	v_mfma_f32_16x16x32_bf16 v[38:41], v[138:141], v[204:207], 0
	v_mfma_f32_16x16x32_bf16 v[30:33], v[160:163], v[204:207], 0
	v_mfma_f32_16x16x32_bf16 v[22:25], v[138:141], v[212:215], 0
	v_mfma_f32_16x16x32_bf16 v[14:17], v[160:163], v[212:215], 0
	v_mfma_f32_16x16x32_bf16 v[62:65], v[156:159], v[188:191], v[62:65]
	v_mfma_f32_16x16x32_bf16 v[58:61], v[164:167], v[188:191], v[58:61]
	v_mfma_f32_16x16x32_bf16 v[54:57], v[156:159], v[196:199], v[54:57]
	v_mfma_f32_16x16x32_bf16 v[46:49], v[164:167], v[196:199], v[46:49]
	v_mfma_f32_16x16x32_bf16 v[38:41], v[156:159], v[208:211], v[38:41]
	v_mfma_f32_16x16x32_bf16 v[30:33], v[164:167], v[208:211], v[30:33]
	v_mfma_f32_16x16x32_bf16 v[22:25], v[156:159], v[216:219], v[22:25]
	v_mfma_f32_16x16x32_bf16 v[14:17], v[164:167], v[216:219], v[14:17]
	s_setprio 0
	s_setprio 1
	v_mfma_f32_16x16x32_bf16 v[50:53], v[168:171], v[184:187], 0
	v_mfma_f32_16x16x32_bf16 v[42:45], v[176:179], v[184:187], 0
	v_mfma_f32_16x16x32_bf16 v[34:37], v[168:171], v[192:195], 0
	v_mfma_f32_16x16x32_bf16 v[26:29], v[176:179], v[192:195], 0
	v_mfma_f32_16x16x32_bf16 v[18:21], v[168:171], v[204:207], 0
	v_mfma_f32_16x16x32_bf16 v[10:13], v[176:179], v[204:207], 0
	v_mfma_f32_16x16x32_bf16 v[6:9], v[168:171], v[212:215], 0
	v_mfma_f32_16x16x32_bf16 v[2:5], v[176:179], v[212:215], 0
	v_mfma_f32_16x16x32_bf16 v[50:53], v[172:175], v[188:191], v[50:53]
	v_mfma_f32_16x16x32_bf16 v[42:45], v[180:183], v[188:191], v[42:45]
	v_mfma_f32_16x16x32_bf16 v[34:37], v[172:175], v[196:199], v[34:37]
	v_mfma_f32_16x16x32_bf16 v[26:29], v[180:183], v[196:199], v[26:29]
	v_mfma_f32_16x16x32_bf16 v[18:21], v[172:175], v[208:211], v[18:21]
	v_mfma_f32_16x16x32_bf16 v[10:13], v[180:183], v[208:211], v[10:13]
	v_mfma_f32_16x16x32_bf16 v[6:9], v[172:175], v[216:219], v[6:9]
	v_mfma_f32_16x16x32_bf16 v[2:5], v[180:183], v[216:219], v[2:5]
	s_setprio 0
	s_barrier
	s_add_i32 s50, 0, 0x18000
	v_add_u32_e32 v155, s50, v143
	s_add_i32 s51, 0, 0x1c000
	ds_read_b128 v[138:141], v155
	ds_read_b128 v[156:159], v155 offset:1024
	ds_read_b128 v[160:163], v155 offset:2048
	ds_read_b128 v[164:167], v155 offset:3072
	v_add_u32_e32 v155, s51, v143
	ds_read_b128 v[168:171], v155
	ds_read_b128 v[172:175], v155 offset:1024
	ds_read_b128 v[176:179], v155 offset:2048
	ds_read_b128 v[180:183], v155 offset:3072
	s_add_u32 s30, s30, 0x40000
	s_addc_u32 s31, s31, 0
	s_mov_b32 m0, s38
	v_lshl_add_u64 v[226:227], s[30:31], 0, v[146:147]
	ds_read_b128 v[184:187], v154 offset:32768
	ds_read_b128 v[188:191], v154 offset:33792
	ds_read_b128 v[192:195], v154 offset:34816
	ds_read_b128 v[196:199], v154 offset:35840
	ds_read_b128 v[204:207], v154 offset:36864
	ds_read_b128 v[208:211], v154 offset:37888
	ds_read_b128 v[212:215], v154 offset:38912
	ds_read_b128 v[216:219], v154 offset:39936
	global_load_lds_dwordx4 v[226:227], off
	v_lshl_add_u64 v[226:227], s[30:31], 0, v[150:151]
	s_mov_b32 m0, s39
	s_nop 0
	global_load_lds_dwordx4 v[226:227], off
	s_waitcnt vmcnt(8)
	s_waitcnt lgkmcnt(0)
	s_barrier
	s_setprio 1
	s_waitcnt lgkmcnt(0)
	v_mfma_f32_16x16x32_bf16 v[126:129], v[138:141], v[184:187], v[126:129]
	v_mfma_f32_16x16x32_bf16 v[122:125], v[160:163], v[184:187], v[122:125]
	v_mfma_f32_16x16x32_bf16 v[114:117], v[138:141], v[192:195], v[114:117]
	v_mfma_f32_16x16x32_bf16 v[106:109], v[160:163], v[192:195], v[106:109]
	v_mfma_f32_16x16x32_bf16 v[98:101], v[138:141], v[204:207], v[98:101]
	v_mfma_f32_16x16x32_bf16 v[90:93], v[160:163], v[204:207], v[90:93]
	v_mfma_f32_16x16x32_bf16 v[82:85], v[138:141], v[212:215], v[82:85]
	v_mfma_f32_16x16x32_bf16 v[74:77], v[160:163], v[212:215], v[74:77]
	v_mfma_f32_16x16x32_bf16 v[126:129], v[156:159], v[188:191], v[126:129]
	v_mfma_f32_16x16x32_bf16 v[122:125], v[164:167], v[188:191], v[122:125]
	v_mfma_f32_16x16x32_bf16 v[114:117], v[156:159], v[196:199], v[114:117]
	v_mfma_f32_16x16x32_bf16 v[106:109], v[164:167], v[196:199], v[106:109]
	v_mfma_f32_16x16x32_bf16 v[98:101], v[156:159], v[208:211], v[98:101]
	v_mfma_f32_16x16x32_bf16 v[90:93], v[164:167], v[208:211], v[90:93]
	v_mfma_f32_16x16x32_bf16 v[82:85], v[156:159], v[216:219], v[82:85]
	v_mfma_f32_16x16x32_bf16 v[74:77], v[164:167], v[216:219], v[74:77]
	s_setprio 0
	s_setprio 1
	v_mfma_f32_16x16x32_bf16 v[118:121], v[168:171], v[184:187], v[118:121]
	v_mfma_f32_16x16x32_bf16 v[110:113], v[176:179], v[184:187], v[110:113]
	v_mfma_f32_16x16x32_bf16 v[102:105], v[168:171], v[192:195], v[102:105]
	v_mfma_f32_16x16x32_bf16 v[94:97], v[176:179], v[192:195], v[94:97]
	v_mfma_f32_16x16x32_bf16 v[86:89], v[168:171], v[204:207], v[86:89]
	v_mfma_f32_16x16x32_bf16 v[78:81], v[176:179], v[204:207], v[78:81]
	v_mfma_f32_16x16x32_bf16 v[70:73], v[168:171], v[212:215], v[70:73]
	v_mfma_f32_16x16x32_bf16 v[66:69], v[176:179], v[212:215], v[66:69]
	v_mfma_f32_16x16x32_bf16 v[118:121], v[172:175], v[188:191], v[118:121]
	v_mfma_f32_16x16x32_bf16 v[110:113], v[180:183], v[188:191], v[110:113]
	v_mfma_f32_16x16x32_bf16 v[102:105], v[172:175], v[196:199], v[102:105]
	v_mfma_f32_16x16x32_bf16 v[94:97], v[180:183], v[196:199], v[94:97]
	v_mfma_f32_16x16x32_bf16 v[86:89], v[172:175], v[208:211], v[86:89]
	v_mfma_f32_16x16x32_bf16 v[78:81], v[180:183], v[208:211], v[78:81]
	v_mfma_f32_16x16x32_bf16 v[70:73], v[172:175], v[216:219], v[70:73]
	v_mfma_f32_16x16x32_bf16 v[66:69], v[180:183], v[216:219], v[66:69]
	s_setprio 0
	s_barrier
; #define PG8_STAGE(bufoff, gbase, voff) do { _Pragma("unroll") for (int _i = 0; _i < 2; ++_i) \
;         __builtin_amdgcn_global_load_lds((const unsigned*)((const char*)(gbase) + (voff)[_i]), (PG8_LAS unsigned*)(lds + (bufoff) + ldsw + _i * 8192), 16, 0, 0); } while (0)
; #define PG8_LDA(dst, b, h) do { _Pragma("unroll") for (int m = 0; m < 4; ++m) _Pragma("unroll") for (int k = 0; k < 2; ++k) dst[m][k] = *(const PG8_LAS bf16x8*)(lds + PG8_SA(b, h) + aoff + m * 2048 + k * 1024); } while (0)
; #define PG8_MMA(ai, bj, At, Bt) do { __builtin_amdgcn_s_setprio(1); _Pragma("unroll") for (int m = 0; m < 4; ++m) _Pragma("unroll") for (int n = 0; n < 2; ++n) _Pragma("unroll") for (int k = 0; k < 2; ++k) \
;         acc[ai][bj][m][n] = __builtin_amdgcn_mfma_f32_16x16x32_bf16(Bt[n][k], At[m][k], acc[ai][bj][m][n], 0, 0, 0); __builtin_amdgcn_s_setprio(0); } while (0)
; #define PG8_WAIT_V(n) asm volatile("s_waitcnt vmcnt(" #n ")" ::: "memory")
; #define PG8_WAIT_L(n) asm volatile("s_waitcnt lgkmcnt(" #n ")" ::: "memory")
; #define PG8_BAR __builtin_amdgcn_s_barrier()
; #define PG8_SCHED __builtin_amdgcn_sched_barrier(0)
; template <class Epi, class Sched, bool ALIGN_EPI = false, bool SP2 = false>
; __device__ __forceinline__ void gemm_phase(PG8_LAS unsigned char* lds, const Gemm g, const Sched& S, const Epi& E) {
;     ...
;             PG8_LDA(At, 1, 1); PG8_STAGE(PG8_SB(1, 0), b3, voffB); PG8_STAGE(PG8_SB(1, 1), b3 + hstep, voffB); PG8_STAGE(PG8_SA(1, 0), a3, voffA);
;             PG8_WAIT_V(8); PG8_WAIT_L(0); PG8_BAR; PG8_MMA(1, 0, At, B0); PG8_MMA(1, 1, At, B1); PG8_BAR; PG8_SCHED;
	s_add_i32 s30, s50, s33
	v_lshl_add_u64 v[200:201], v[200:201], 0, s[6:7]
	s_mov_b32 m0, s30
	ds_read_b128 v[184:187], v154 offset:49152
	ds_read_b128 v[188:191], v154 offset:50176
	ds_read_b128 v[192:195], v154 offset:51200
	ds_read_b128 v[196:199], v154 offset:52224
	ds_read_b128 v[204:207], v154 offset:53248
	ds_read_b128 v[208:211], v154 offset:54272
	ds_read_b128 v[212:215], v154 offset:55296
	ds_read_b128 v[216:219], v154 offset:56320
	global_load_lds_dwordx4 v[200:201], off
	s_add_i32 m0, s30, 0x2000
	s_add_u32 s28, s28, 0x40080
	v_lshl_add_u64 v[200:201], v[220:221], 0, s[6:7]
	s_addc_u32 s29, s29, 0
	s_add_i32 s30, s51, s33
	global_load_lds_dwordx4 v[200:201], off
	v_lshl_add_u64 v[200:201], s[28:29], 0, v[148:149]
	s_mov_b32 m0, s30
	s_nop 0
	global_load_lds_dwordx4 v[200:201], off
	v_lshl_add_u64 v[200:201], s[28:29], 0, v[152:153]
	s_add_i32 m0, s30, 0x2000
	s_nop 0
	global_load_lds_dwordx4 v[200:201], off
	v_lshl_add_u64 v[200:201], v[222:223], 0, s[6:7]
	s_mov_b32 m0, s40
	s_nop 0
	global_load_lds_dwordx4 v[200:201], off
	v_lshl_add_u64 v[200:201], v[224:225], 0, s[6:7]
	s_mov_b32 m0, s41
	s_nop 0
	global_load_lds_dwordx4 v[200:201], off
	s_waitcnt vmcnt(8)
	s_waitcnt lgkmcnt(0)
	s_barrier
	s_setprio 1
	s_waitcnt lgkmcnt(0)
	v_mfma_f32_16x16x32_bf16 v[62:65], v[138:141], v[184:187], v[62:65]
	v_mfma_f32_16x16x32_bf16 v[58:61], v[160:163], v[184:187], v[58:61]
	v_mfma_f32_16x16x32_bf16 v[54:57], v[138:141], v[192:195], v[54:57]
	v_mfma_f32_16x16x32_bf16 v[46:49], v[160:163], v[192:195], v[46:49]
	v_mfma_f32_16x16x32_bf16 v[38:41], v[138:141], v[204:207], v[38:41]
	v_mfma_f32_16x16x32_bf16 v[30:33], v[160:163], v[204:207], v[30:33]
	v_mfma_f32_16x16x32_bf16 v[22:25], v[138:141], v[212:215], v[22:25]
	v_mfma_f32_16x16x32_bf16 v[14:17], v[160:163], v[212:215], v[14:17]
	v_mfma_f32_16x16x32_bf16 v[62:65], v[156:159], v[188:191], v[62:65]
	v_mfma_f32_16x16x32_bf16 v[58:61], v[164:167], v[188:191], v[58:61]
	v_mfma_f32_16x16x32_bf16 v[54:57], v[156:159], v[196:199], v[54:57]
	v_mfma_f32_16x16x32_bf16 v[46:49], v[164:167], v[196:199], v[46:49]
	v_mfma_f32_16x16x32_bf16 v[38:41], v[156:159], v[208:211], v[38:41]
	v_mfma_f32_16x16x32_bf16 v[30:33], v[164:167], v[208:211], v[30:33]
	v_mfma_f32_16x16x32_bf16 v[22:25], v[156:159], v[216:219], v[22:25]
	v_mfma_f32_16x16x32_bf16 v[14:17], v[164:167], v[216:219], v[14:17]
	s_setprio 0
	s_setprio 1
	v_mfma_f32_16x16x32_bf16 v[50:53], v[168:171], v[184:187], v[50:53]
	v_mfma_f32_16x16x32_bf16 v[42:45], v[176:179], v[184:187], v[42:45]
	v_mfma_f32_16x16x32_bf16 v[34:37], v[168:171], v[192:195], v[34:37]
	v_mfma_f32_16x16x32_bf16 v[26:29], v[176:179], v[192:195], v[26:29]
	v_mfma_f32_16x16x32_bf16 v[18:21], v[168:171], v[204:207], v[18:21]
	v_mfma_f32_16x16x32_bf16 v[10:13], v[176:179], v[204:207], v[10:13]
	v_mfma_f32_16x16x32_bf16 v[6:9], v[168:171], v[212:215], v[6:9]
	v_mfma_f32_16x16x32_bf16 v[2:5], v[176:179], v[212:215], v[2:5]
	v_mfma_f32_16x16x32_bf16 v[50:53], v[172:175], v[188:191], v[50:53]
	v_mfma_f32_16x16x32_bf16 v[42:45], v[180:183], v[188:191], v[42:45]
	v_mfma_f32_16x16x32_bf16 v[34:37], v[172:175], v[196:199], v[34:37]
	v_mfma_f32_16x16x32_bf16 v[26:29], v[180:183], v[196:199], v[26:29]
	v_mfma_f32_16x16x32_bf16 v[18:21], v[172:175], v[208:211], v[18:21]
	v_mfma_f32_16x16x32_bf16 v[10:13], v[180:183], v[208:211], v[10:13]
	v_mfma_f32_16x16x32_bf16 v[6:9], v[172:175], v[216:219], v[6:9]
	v_mfma_f32_16x16x32_bf16 v[2:5], v[180:183], v[216:219], v[2:5]
	s_setprio 0
	s_barrier
	s_add_i32 s49, s49, 2
	s_add_u32 s26, s26, 0x100
	s_addc_u32 s27, s27, 0
	s_add_u32 s47, s47, 0x100
	s_addc_u32 s48, s48, 0
	s_cmp_gt_u32 s49, 13
	s_cbranch_scc0 .LBB0_328
	s_branch .Lkexit1

; #define PG8_BAR __builtin_amdgcn_s_barrier()
; template <class Epi, class Sched, bool ALIGN_EPI = false, bool SP2 = false>
; __device__ __forceinline__ void gemm_phase(PG8_LAS unsigned char* lds, const Gemm g, const Sched& S, const Epi& E) {
;     ...
;         if constexpr (ALIGN_EPI) { if (wr == 0) PG8_BAR; }
;         if constexpr (!Epi::AFTER_DRAIN) { E(acc, cur, wr, wc, fr, fq); S.done(cur); }
.Lkexit1:
	s_and_b64 vcc, exec, s[10:11]
	s_cbranch_vccz .LBB0_331
	s_barrier

; #define PG8_STAGE(bufoff, gbase, voff) do { _Pragma("unroll") for (int _i = 0; _i < 2; ++_i) \
;         __builtin_amdgcn_global_load_lds((const unsigned*)((const char*)(gbase) + (voff)[_i]), (PG8_LAS unsigned*)(lds + (bufoff) + ldsw + _i * 8192), 16, 0, 0); } while (0)
; #define PG8_LDA(dst, b, h) do { _Pragma("unroll") for (int m = 0; m < 4; ++m) _Pragma("unroll") for (int k = 0; k < 2; ++k) dst[m][k] = *(const PG8_LAS bf16x8*)(lds + PG8_SA(b, h) + aoff + m * 2048 + k * 1024); } while (0)
; #define PG8_LDB(dst, b, h) do { _Pragma("unroll") for (int n = 0; n < 2; ++n) _Pragma("unroll") for (int k = 0; k < 2; ++k) dst[n][k] = *(const PG8_LAS bf16x8*)(lds + PG8_SB(b, h) + boff + n * 2048 + k * 1024); } while (0)
; #define PG8_MMA(ai, bj, At, Bt) do { __builtin_amdgcn_s_setprio(1); _Pragma("unroll") for (int m = 0; m < 4; ++m) _Pragma("unroll") for (int n = 0; n < 2; ++n) _Pragma("unroll") for (int k = 0; k < 2; ++k) \
;         acc[ai][bj][m][n] = __builtin_amdgcn_mfma_f32_16x16x32_bf16(Bt[n][k], At[m][k], acc[ai][bj][m][n], 0, 0, 0); __builtin_amdgcn_s_setprio(0); } while (0)
; #define PG8_WAIT_V(n) asm volatile("s_waitcnt vmcnt(" #n ")" ::: "memory")
; #define PG8_WAIT_L(n) asm volatile("s_waitcnt lgkmcnt(" #n ")" ::: "memory")
; #define PG8_BAR __builtin_amdgcn_s_barrier()
; #define PG8_SCHED __builtin_amdgcn_sched_barrier(0)
; template <class Epi, class Sched, bool ALIGN_EPI = false, bool SP2 = false>
; __device__ __forceinline__ void gemm_phase(PG8_LAS unsigned char* lds, const Gemm g, const Sched& S, const Epi& E) {
;     ...
;             PG8_LDB(B0, 0, 0); PG8_LDB(B1, 0, 1); PG8_SCHED; PG8_LDA(At, 0, 0); PG8_STAGE(PG8_SA(1, 1), a1 + hstep, voffA);
;             PG8_WAIT_V(8); PG8_WAIT_L(0); PG8_BAR; PG8_MMA(0, 0, At, B0); PG8_MMA(0, 1, At, B1); PG8_BAR; PG8_SCHED;
;             PG8_LDA(At, 0, 1); PG8_STAGE(PG8_SB(0, 0), b2, voffB); PG8_STAGE(PG8_SB(0, 1), b2 + hstep, voffB); PG8_STAGE(PG8_SA(0, 0), a2, voffA);
;             PG8_WAIT_V(8); PG8_WAIT_L(0); PG8_BAR; PG8_MMA(1, 0, At, B0); PG8_MMA(1, 1, At, B1); PG8_BAR; PG8_SCHED;
.LBB0_770:
	s_ashr_i32 s19, s18, 31
	s_lshl_b64 s[2:3], s[18:19], 19
	s_add_u32 s24, s38, s2
	s_addc_u32 s25, s39, s3
	s_and_b64 s[2:3], s[4:5], exec
	s_cselect_b32 s2, s25, s31
	s_cselect_b32 s3, s24, s30
	s_ashr_i32 s17, s16, 31
	s_lshl_b64 s[26:27], s[16:17], 19
	s_add_u32 s26, s94, s26
	s_addc_u32 s27, s95, s27
	s_and_b64 s[40:41], s[4:5], exec
	s_cselect_b32 s17, s27, s35
	s_cselect_b32 s19, s26, s34
	s_add_u32 s30, s30, 0x40080
	s_addc_u32 s31, s31, 0
	s_add_u32 s29, s34, 0x100
	s_addc_u32 s54, s35, 0
	s_mov_b32 s55, -2
	s_waitcnt lgkmcnt(0)
	ds_read_b128 v[114:117], v248
	ds_read_b128 v[118:121], v248 offset:1024
	ds_read_b128 v[126:129], v248 offset:2048
	ds_read_b128 v[130:133], v248 offset:3072
	ds_read_b128 v[138:141], v249
	ds_read_b128 v[142:145], v249 offset:1024
	ds_read_b128 v[146:149], v249 offset:2048
	ds_read_b128 v[154:157], v249 offset:3072
	s_add_u32 s34, s30, 0xfffc0080
	s_addc_u32 s35, s31, -1
	s_cmp_eq_u32 s55, 12
	s_cselect_b32 s41, s2, s35
	s_cselect_b32 s40, s3, s34
	s_cselect_b32 s35, s17, s54
	s_cselect_b32 s34, s19, s29
	v_lshl_add_u64 v[208:209], s[30:31], 0, v[204:205]
	s_add_i32 m0, s42, 0xc000
	ds_read_b128 v[162:165], v250
	ds_read_b128 v[166:169], v250 offset:1024
	ds_read_b128 v[170:173], v250 offset:2048
	ds_read_b128 v[174:177], v250 offset:3072
	ds_read_b128 v[178:181], v250 offset:4096
	ds_read_b128 v[182:185], v250 offset:5120
	ds_read_b128 v[186:189], v250 offset:6144
	ds_read_b128 v[190:193], v250 offset:7168
	global_load_lds_dwordx4 v[208:209], off
	v_lshl_add_u64 v[208:209], s[30:31], 0, v[206:207]
	s_add_i32 m0, s42, 0xe000
	s_nop 0
	global_load_lds_dwordx4 v[208:209], off
	s_waitcnt vmcnt(8)
	s_waitcnt lgkmcnt(0)
	s_barrier
	s_setprio 1
	s_waitcnt lgkmcnt(0)
	v_mfma_f32_16x16x32_bf16 v[158:161], v[114:117], v[162:165], 0
	v_mfma_f32_16x16x32_bf16 v[150:153], v[126:129], v[162:165], 0
	v_mfma_f32_16x16x32_bf16 v[110:113], v[114:117], v[170:173], 0
	v_mfma_f32_16x16x32_bf16 v[106:109], v[126:129], v[170:173], 0
	v_mfma_f32_16x16x32_bf16 v[94:97], v[114:117], v[178:181], 0
	v_mfma_f32_16x16x32_bf16 v[90:93], v[126:129], v[178:181], 0
	v_mfma_f32_16x16x32_bf16 v[78:81], v[114:117], v[186:189], 0
	v_mfma_f32_16x16x32_bf16 v[74:77], v[126:129], v[186:189], 0
	v_mfma_f32_16x16x32_bf16 v[158:161], v[118:121], v[166:169], v[158:161]
	v_mfma_f32_16x16x32_bf16 v[150:153], v[130:133], v[166:169], v[150:153]
	v_mfma_f32_16x16x32_bf16 v[110:113], v[118:121], v[174:177], v[110:113]
	v_mfma_f32_16x16x32_bf16 v[106:109], v[130:133], v[174:177], v[106:109]
	v_mfma_f32_16x16x32_bf16 v[94:97], v[118:121], v[182:185], v[94:97]
	v_mfma_f32_16x16x32_bf16 v[90:93], v[130:133], v[182:185], v[90:93]
	v_mfma_f32_16x16x32_bf16 v[78:81], v[118:121], v[190:193], v[78:81]
	v_mfma_f32_16x16x32_bf16 v[74:77], v[130:133], v[190:193], v[74:77]
	s_setprio 0
	s_setprio 1
	v_mfma_f32_16x16x32_bf16 v[134:137], v[138:141], v[162:165], 0
	v_mfma_f32_16x16x32_bf16 v[122:125], v[146:149], v[162:165], 0
	v_mfma_f32_16x16x32_bf16 v[102:105], v[138:141], v[170:173], 0
	v_mfma_f32_16x16x32_bf16 v[98:101], v[146:149], v[170:173], 0
	v_mfma_f32_16x16x32_bf16 v[86:89], v[138:141], v[178:181], 0
	v_mfma_f32_16x16x32_bf16 v[82:85], v[146:149], v[178:181], 0
	v_mfma_f32_16x16x32_bf16 v[70:73], v[138:141], v[186:189], 0
	v_mfma_f32_16x16x32_bf16 v[66:69], v[146:149], v[186:189], 0
	v_mfma_f32_16x16x32_bf16 v[134:137], v[142:145], v[166:169], v[134:137]
	v_mfma_f32_16x16x32_bf16 v[122:125], v[154:157], v[166:169], v[122:125]
	v_mfma_f32_16x16x32_bf16 v[102:105], v[142:145], v[174:177], v[102:105]
	v_mfma_f32_16x16x32_bf16 v[98:101], v[154:157], v[174:177], v[98:101]
	v_mfma_f32_16x16x32_bf16 v[86:89], v[142:145], v[182:185], v[86:89]
	v_mfma_f32_16x16x32_bf16 v[82:85], v[154:157], v[182:185], v[82:85]
	v_mfma_f32_16x16x32_bf16 v[70:73], v[142:145], v[190:193], v[70:73]
	v_mfma_f32_16x16x32_bf16 v[66:69], v[154:157], v[190:193], v[66:69]
	s_setprio 0
	s_barrier
	s_add_i32 s56, s51, s33
	v_lshl_add_u64 v[208:209], s[34:35], 0, v[196:197]
	s_mov_b32 m0, s56
	ds_read_b128 v[162:165], v250 offset:16384
	ds_read_b128 v[166:169], v250 offset:17408
	ds_read_b128 v[170:173], v250 offset:18432
	ds_read_b128 v[174:177], v250 offset:19456
	ds_read_b128 v[178:181], v250 offset:20480
	ds_read_b128 v[182:185], v250 offset:21504
	ds_read_b128 v[186:189], v250 offset:22528
	ds_read_b128 v[190:193], v250 offset:23552
	global_load_lds_dwordx4 v[208:209], off
	s_add_i32 m0, s56, 0x2000
	s_add_u32 s56, s34, 0x40000
	v_lshl_add_u64 v[210:211], s[34:35], 0, v[200:201]
	s_addc_u32 s57, s35, 0
	s_add_i32 s58, s52, s33
	global_load_lds_dwordx4 v[210:211], off
	v_lshl_add_u64 v[212:213], s[56:57], 0, v[196:197]
	s_mov_b32 m0, s58
	v_lshl_add_u64 v[214:215], s[40:41], 0, v[198:199]
	global_load_lds_dwordx4 v[212:213], off
	v_lshl_add_u64 v[212:213], s[56:57], 0, v[200:201]
	s_add_i32 m0, s58, 0x2000
	s_nop 0
	global_load_lds_dwordx4 v[212:213], off
	v_lshl_add_u64 v[212:213], s[40:41], 0, v[194:195]
	s_mov_b32 m0, s42
	s_nop 0
	global_load_lds_dwordx4 v[212:213], off
	s_mov_b32 m0, s43
	s_nop 0
	global_load_lds_dwordx4 v[214:215], off
	s_waitcnt vmcnt(8)
	s_waitcnt lgkmcnt(0)
	s_barrier
; #define PG8_STAGE(bufoff, gbase, voff) do { _Pragma("unroll") for (int _i = 0; _i < 2; ++_i) \
;         __builtin_amdgcn_global_load_lds((const unsigned*)((const char*)(gbase) + (voff)[_i]), (PG8_LAS unsigned*)(lds + (bufoff) + ldsw + _i * 8192), 16, 0, 0); } while (0)
; #define PG8_LDA(dst, b, h) do { _Pragma("unroll") for (int m = 0; m < 4; ++m) _Pragma("unroll") for (int k = 0; k < 2; ++k) dst[m][k] = *(const PG8_LAS bf16x8*)(lds + PG8_SA(b, h) + aoff + m * 2048 + k * 1024); } while (0)
; #define PG8_LDB(dst, b, h) do { _Pragma("unroll") for (int n = 0; n < 2; ++n) _Pragma("unroll") for (int k = 0; k < 2; ++k) dst[n][k] = *(const PG8_LAS bf16x8*)(lds + PG8_SB(b, h) + boff + n * 2048 + k * 1024); } while (0)
; #define PG8_MMA(ai, bj, At, Bt) do { __builtin_amdgcn_s_setprio(1); _Pragma("unroll") for (int m = 0; m < 4; ++m) _Pragma("unroll") for (int n = 0; n < 2; ++n) _Pragma("unroll") for (int k = 0; k < 2; ++k) \
;         acc[ai][bj][m][n] = __builtin_amdgcn_mfma_f32_16x16x32_bf16(Bt[n][k], At[m][k], acc[ai][bj][m][n], 0, 0, 0); __builtin_amdgcn_s_setprio(0); } while (0)
; #define PG8_WAIT_V(n) asm volatile("s_waitcnt vmcnt(" #n ")" ::: "memory")
; #define PG8_WAIT_L(n) asm volatile("s_waitcnt lgkmcnt(" #n ")" ::: "memory")
; #define PG8_BAR __builtin_amdgcn_s_barrier()
; #define PG8_SCHED __builtin_amdgcn_sched_barrier(0)
; template <class Epi, class Sched, bool ALIGN_EPI = false, bool SP2 = false>
; __device__ __forceinline__ void gemm_phase(PG8_LAS unsigned char* lds, const Gemm g, const Sched& S, const Epi& E) {
;     ...
;             PG8_WAIT_V(8); PG8_WAIT_L(0); PG8_BAR; PG8_MMA(1, 0, At, B0); PG8_MMA(1, 1, At, B1); PG8_BAR; PG8_SCHED;
;             PG8_LDB(B0, 1, 0); PG8_LDB(B1, 1, 1); PG8_SCHED; PG8_LDA(At, 1, 0); PG8_STAGE(PG8_SA(0, 1), a2 + hstep, voffA);
;             PG8_WAIT_V(8); PG8_WAIT_L(0); PG8_BAR; PG8_MMA(0, 0, At, B0); PG8_MMA(0, 1, At, B1); PG8_BAR; PG8_SCHED;
	s_setprio 1
	s_waitcnt lgkmcnt(0)
	v_mfma_f32_16x16x32_bf16 v[62:65], v[114:117], v[162:165], 0
	v_mfma_f32_16x16x32_bf16 v[58:61], v[126:129], v[162:165], 0
	v_mfma_f32_16x16x32_bf16 v[46:49], v[114:117], v[170:173], 0
	v_mfma_f32_16x16x32_bf16 v[42:45], v[126:129], v[170:173], 0
	v_mfma_f32_16x16x32_bf16 v[30:33], v[114:117], v[178:181], 0
	v_mfma_f32_16x16x32_bf16 v[26:29], v[126:129], v[178:181], 0
	v_mfma_f32_16x16x32_bf16 v[14:17], v[114:117], v[186:189], 0
	v_mfma_f32_16x16x32_bf16 v[10:13], v[126:129], v[186:189], 0
	v_mfma_f32_16x16x32_bf16 v[62:65], v[118:121], v[166:169], v[62:65]
	v_mfma_f32_16x16x32_bf16 v[58:61], v[130:133], v[166:169], v[58:61]
	v_mfma_f32_16x16x32_bf16 v[46:49], v[118:121], v[174:177], v[46:49]
	v_mfma_f32_16x16x32_bf16 v[42:45], v[130:133], v[174:177], v[42:45]
	v_mfma_f32_16x16x32_bf16 v[30:33], v[118:121], v[182:185], v[30:33]
	v_mfma_f32_16x16x32_bf16 v[26:29], v[130:133], v[182:185], v[26:29]
	v_mfma_f32_16x16x32_bf16 v[14:17], v[118:121], v[190:193], v[14:17]
	v_mfma_f32_16x16x32_bf16 v[10:13], v[130:133], v[190:193], v[10:13]
	s_setprio 0
	s_setprio 1
	v_mfma_f32_16x16x32_bf16 v[54:57], v[138:141], v[162:165], 0
	v_mfma_f32_16x16x32_bf16 v[50:53], v[146:149], v[162:165], 0
	v_mfma_f32_16x16x32_bf16 v[38:41], v[138:141], v[170:173], 0
	v_mfma_f32_16x16x32_bf16 v[34:37], v[146:149], v[170:173], 0
	v_mfma_f32_16x16x32_bf16 v[22:25], v[138:141], v[178:181], 0
	v_mfma_f32_16x16x32_bf16 v[18:21], v[146:149], v[178:181], 0
	v_mfma_f32_16x16x32_bf16 v[6:9], v[138:141], v[186:189], 0
	v_mfma_f32_16x16x32_bf16 v[2:5], v[146:149], v[186:189], 0
	v_mfma_f32_16x16x32_bf16 v[54:57], v[142:145], v[166:169], v[54:57]
	v_mfma_f32_16x16x32_bf16 v[50:53], v[154:157], v[166:169], v[50:53]
	v_mfma_f32_16x16x32_bf16 v[38:41], v[142:145], v[174:177], v[38:41]
	v_mfma_f32_16x16x32_bf16 v[34:37], v[154:157], v[174:177], v[34:37]
	v_mfma_f32_16x16x32_bf16 v[22:25], v[142:145], v[182:185], v[22:25]
	v_mfma_f32_16x16x32_bf16 v[18:21], v[154:157], v[182:185], v[18:21]
	v_mfma_f32_16x16x32_bf16 v[6:9], v[142:145], v[190:193], v[6:9]
	v_mfma_f32_16x16x32_bf16 v[2:5], v[154:157], v[190:193], v[2:5]
	s_setprio 0
	s_barrier
	s_add_i32 s56, 0, 0x18000
	s_add_i32 s57, 0, 0x1c000
	v_add_u32_e32 v130, s56, v246
	v_add_u32_e32 v154, s57, v246
	ds_read_b128 v[114:117], v130
	ds_read_b128 v[118:121], v130 offset:1024
	ds_read_b128 v[126:129], v130 offset:2048
	ds_read_b128 v[130:133], v130 offset:3072
	ds_read_b128 v[138:141], v154
	ds_read_b128 v[142:145], v154 offset:1024
	ds_read_b128 v[146:149], v154 offset:2048
	ds_read_b128 v[154:157], v154 offset:3072
	s_add_u32 s40, s40, 0x40000
	s_addc_u32 s41, s41, 0
	s_mov_b32 m0, s44
	v_lshl_add_u64 v[216:217], s[40:41], 0, v[194:195]
	ds_read_b128 v[162:165], v250 offset:32768
	ds_read_b128 v[166:169], v250 offset:33792
	ds_read_b128 v[170:173], v250 offset:34816
	ds_read_b128 v[174:177], v250 offset:35840
	ds_read_b128 v[178:181], v250 offset:36864
	ds_read_b128 v[182:185], v250 offset:37888
	ds_read_b128 v[186:189], v250 offset:38912
	ds_read_b128 v[190:193], v250 offset:39936
	global_load_lds_dwordx4 v[216:217], off
	v_lshl_add_u64 v[216:217], s[40:41], 0, v[198:199]
	s_mov_b32 m0, s45
	s_nop 0
	global_load_lds_dwordx4 v[216:217], off
	s_waitcnt vmcnt(8)
	s_waitcnt lgkmcnt(0)
	s_barrier
	s_setprio 1
	s_waitcnt lgkmcnt(0)
	v_mfma_f32_16x16x32_bf16 v[158:161], v[114:117], v[162:165], v[158:161]
	v_mfma_f32_16x16x32_bf16 v[150:153], v[126:129], v[162:165], v[150:153]
	v_mfma_f32_16x16x32_bf16 v[110:113], v[114:117], v[170:173], v[110:113]
	v_mfma_f32_16x16x32_bf16 v[106:109], v[126:129], v[170:173], v[106:109]
	v_mfma_f32_16x16x32_bf16 v[94:97], v[114:117], v[178:181], v[94:97]
	v_mfma_f32_16x16x32_bf16 v[90:93], v[126:129], v[178:181], v[90:93]
	v_mfma_f32_16x16x32_bf16 v[78:81], v[114:117], v[186:189], v[78:81]
	v_mfma_f32_16x16x32_bf16 v[74:77], v[126:129], v[186:189], v[74:77]
	v_mfma_f32_16x16x32_bf16 v[158:161], v[118:121], v[166:169], v[158:161]
	v_mfma_f32_16x16x32_bf16 v[150:153], v[130:133], v[166:169], v[150:153]
	v_mfma_f32_16x16x32_bf16 v[110:113], v[118:121], v[174:177], v[110:113]
	v_mfma_f32_16x16x32_bf16 v[106:109], v[130:133], v[174:177], v[106:109]
	v_mfma_f32_16x16x32_bf16 v[94:97], v[118:121], v[182:185], v[94:97]
	v_mfma_f32_16x16x32_bf16 v[90:93], v[130:133], v[182:185], v[90:93]
	v_mfma_f32_16x16x32_bf16 v[78:81], v[118:121], v[190:193], v[78:81]
	v_mfma_f32_16x16x32_bf16 v[74:77], v[130:133], v[190:193], v[74:77]
	s_setprio 0
	s_setprio 1
	v_mfma_f32_16x16x32_bf16 v[134:137], v[138:141], v[162:165], v[134:137]
	v_mfma_f32_16x16x32_bf16 v[122:125], v[146:149], v[162:165], v[122:125]
	v_mfma_f32_16x16x32_bf16 v[102:105], v[138:141], v[170:173], v[102:105]
	v_mfma_f32_16x16x32_bf16 v[98:101], v[146:149], v[170:173], v[98:101]
	v_mfma_f32_16x16x32_bf16 v[86:89], v[138:141], v[178:181], v[86:89]
	v_mfma_f32_16x16x32_bf16 v[82:85], v[146:149], v[178:181], v[82:85]
	v_mfma_f32_16x16x32_bf16 v[70:73], v[138:141], v[186:189], v[70:73]
	v_mfma_f32_16x16x32_bf16 v[66:69], v[146:149], v[186:189], v[66:69]
	v_mfma_f32_16x16x32_bf16 v[134:137], v[142:145], v[166:169], v[134:137]
	v_mfma_f32_16x16x32_bf16 v[122:125], v[154:157], v[166:169], v[122:125]
	v_mfma_f32_16x16x32_bf16 v[102:105], v[142:145], v[174:177], v[102:105]
	v_mfma_f32_16x16x32_bf16 v[98:101], v[154:157], v[174:177], v[98:101]
	v_mfma_f32_16x16x32_bf16 v[86:89], v[142:145], v[182:185], v[86:89]
	v_mfma_f32_16x16x32_bf16 v[82:85], v[154:157], v[182:185], v[82:85]
	v_mfma_f32_16x16x32_bf16 v[70:73], v[142:145], v[190:193], v[70:73]
	v_mfma_f32_16x16x32_bf16 v[66:69], v[154:157], v[190:193], v[66:69]
	s_setprio 0
	s_barrier
; #define PG8_STAGE(bufoff, gbase, voff) do { _Pragma("unroll") for (int _i = 0; _i < 2; ++_i) \
;         __builtin_amdgcn_global_load_lds((const unsigned*)((const char*)(gbase) + (voff)[_i]), (PG8_LAS unsigned*)(lds + (bufoff) + ldsw + _i * 8192), 16, 0, 0); } while (0)
; #define PG8_LDA(dst, b, h) do { _Pragma("unroll") for (int m = 0; m < 4; ++m) _Pragma("unroll") for (int k = 0; k < 2; ++k) dst[m][k] = *(const PG8_LAS bf16x8*)(lds + PG8_SA(b, h) + aoff + m * 2048 + k * 1024); } while (0)
; #define PG8_MMA(ai, bj, At, Bt) do { __builtin_amdgcn_s_setprio(1); _Pragma("unroll") for (int m = 0; m < 4; ++m) _Pragma("unroll") for (int n = 0; n < 2; ++n) _Pragma("unroll") for (int k = 0; k < 2; ++k) \
;         acc[ai][bj][m][n] = __builtin_amdgcn_mfma_f32_16x16x32_bf16(Bt[n][k], At[m][k], acc[ai][bj][m][n], 0, 0, 0); __builtin_amdgcn_s_setprio(0); } while (0)
; #define PG8_WAIT_V(n) asm volatile("s_waitcnt vmcnt(" #n ")" ::: "memory")
; #define PG8_WAIT_L(n) asm volatile("s_waitcnt lgkmcnt(" #n ")" ::: "memory")
; #define PG8_BAR __builtin_amdgcn_s_barrier()
; #define PG8_SCHED __builtin_amdgcn_sched_barrier(0)
; template <class Epi, class Sched, bool ALIGN_EPI = false, bool SP2 = false>
; __device__ __forceinline__ void gemm_phase(PG8_LAS unsigned char* lds, const Gemm g, const Sched& S, const Epi& E) {
;     ...
;             PG8_LDA(At, 1, 1); PG8_STAGE(PG8_SB(1, 0), b3, voffB); PG8_STAGE(PG8_SB(1, 1), b3 + hstep, voffB); PG8_STAGE(PG8_SA(1, 0), a3, voffA);
;             PG8_WAIT_V(8); PG8_WAIT_L(0); PG8_BAR; PG8_MMA(1, 0, At, B0); PG8_MMA(1, 1, At, B1); PG8_BAR; PG8_SCHED;
	s_add_i32 s40, s56, s33
	v_lshl_add_u64 v[208:209], v[208:209], 0, s[12:13]
	s_mov_b32 m0, s40
	ds_read_b128 v[162:165], v250 offset:49152
	ds_read_b128 v[166:169], v250 offset:50176
	ds_read_b128 v[170:173], v250 offset:51200
	ds_read_b128 v[174:177], v250 offset:52224
	ds_read_b128 v[178:181], v250 offset:53248
	ds_read_b128 v[182:185], v250 offset:54272
	ds_read_b128 v[186:189], v250 offset:55296
	ds_read_b128 v[190:193], v250 offset:56320
	global_load_lds_dwordx4 v[208:209], off
	s_add_i32 m0, s40, 0x2000
	s_add_u32 s34, s34, 0x40080
	v_lshl_add_u64 v[208:209], v[210:211], 0, s[12:13]
	s_addc_u32 s35, s35, 0
	s_add_i32 s40, s57, s33
	global_load_lds_dwordx4 v[208:209], off
	v_lshl_add_u64 v[208:209], s[34:35], 0, v[196:197]
	s_mov_b32 m0, s40
	s_nop 0
	global_load_lds_dwordx4 v[208:209], off
	v_lshl_add_u64 v[208:209], s[34:35], 0, v[200:201]
	s_add_i32 m0, s40, 0x2000
	s_nop 0
	global_load_lds_dwordx4 v[208:209], off
	v_lshl_add_u64 v[208:209], v[212:213], 0, s[12:13]
	s_mov_b32 m0, s47
	s_nop 0
	global_load_lds_dwordx4 v[208:209], off
	v_lshl_add_u64 v[208:209], v[214:215], 0, s[12:13]
	s_mov_b32 m0, s48
	s_nop 0
	global_load_lds_dwordx4 v[208:209], off
	s_waitcnt vmcnt(8)
	s_waitcnt lgkmcnt(0)
	s_barrier
	s_setprio 1
	s_waitcnt lgkmcnt(0)
	v_mfma_f32_16x16x32_bf16 v[62:65], v[114:117], v[162:165], v[62:65]
	v_mfma_f32_16x16x32_bf16 v[58:61], v[126:129], v[162:165], v[58:61]
	v_mfma_f32_16x16x32_bf16 v[46:49], v[114:117], v[170:173], v[46:49]
	v_mfma_f32_16x16x32_bf16 v[42:45], v[126:129], v[170:173], v[42:45]
	v_mfma_f32_16x16x32_bf16 v[30:33], v[114:117], v[178:181], v[30:33]
	v_mfma_f32_16x16x32_bf16 v[26:29], v[126:129], v[178:181], v[26:29]
	v_mfma_f32_16x16x32_bf16 v[14:17], v[114:117], v[186:189], v[14:17]
	v_mfma_f32_16x16x32_bf16 v[10:13], v[126:129], v[186:189], v[10:13]
	v_mfma_f32_16x16x32_bf16 v[62:65], v[118:121], v[166:169], v[62:65]
	v_mfma_f32_16x16x32_bf16 v[58:61], v[130:133], v[166:169], v[58:61]
	v_mfma_f32_16x16x32_bf16 v[46:49], v[118:121], v[174:177], v[46:49]
	v_mfma_f32_16x16x32_bf16 v[42:45], v[130:133], v[174:177], v[42:45]
	v_mfma_f32_16x16x32_bf16 v[30:33], v[118:121], v[182:185], v[30:33]
	v_mfma_f32_16x16x32_bf16 v[26:29], v[130:133], v[182:185], v[26:29]
	v_mfma_f32_16x16x32_bf16 v[14:17], v[118:121], v[190:193], v[14:17]
	v_mfma_f32_16x16x32_bf16 v[10:13], v[130:133], v[190:193], v[10:13]
	s_setprio 0
	s_setprio 1
	v_mfma_f32_16x16x32_bf16 v[54:57], v[138:141], v[162:165], v[54:57]
	v_mfma_f32_16x16x32_bf16 v[50:53], v[146:149], v[162:165], v[50:53]
	v_mfma_f32_16x16x32_bf16 v[38:41], v[138:141], v[170:173], v[38:41]
	v_mfma_f32_16x16x32_bf16 v[34:37], v[146:149], v[170:173], v[34:37]
	v_mfma_f32_16x16x32_bf16 v[22:25], v[138:141], v[178:181], v[22:25]
	v_mfma_f32_16x16x32_bf16 v[18:21], v[146:149], v[178:181], v[18:21]
	v_mfma_f32_16x16x32_bf16 v[6:9], v[138:141], v[186:189], v[6:9]
	v_mfma_f32_16x16x32_bf16 v[2:5], v[146:149], v[186:189], v[2:5]
	v_mfma_f32_16x16x32_bf16 v[54:57], v[142:145], v[166:169], v[54:57]
	v_mfma_f32_16x16x32_bf16 v[50:53], v[154:157], v[166:169], v[50:53]
	v_mfma_f32_16x16x32_bf16 v[38:41], v[142:145], v[174:177], v[38:41]
	v_mfma_f32_16x16x32_bf16 v[34:37], v[154:157], v[174:177], v[34:37]
	v_mfma_f32_16x16x32_bf16 v[22:25], v[142:145], v[182:185], v[22:25]
	v_mfma_f32_16x16x32_bf16 v[18:21], v[154:157], v[182:185], v[18:21]
	v_mfma_f32_16x16x32_bf16 v[6:9], v[142:145], v[190:193], v[6:9]
	v_mfma_f32_16x16x32_bf16 v[2:5], v[154:157], v[190:193], v[2:5]
	s_setprio 0
	s_barrier
	s_add_i32 s55, s55, 2
	s_add_u32 s30, s30, 0x100
	s_addc_u32 s31, s31, 0
	s_add_u32 s29, s29, 0x100
	s_addc_u32 s54, s54, 0
	s_cmp_gt_u32 s55, 13
	s_cbranch_scc0 .LBB0_771
	s_branch .Lkexit2

; #define PG8_BAR __builtin_amdgcn_s_barrier()
; template <class Epi, class Sched, bool ALIGN_EPI = false, bool SP2 = false>
; __device__ __forceinline__ void gemm_phase(PG8_LAS unsigned char* lds, const Gemm g, const Sched& S, const Epi& E) {
;     ...
;         if constexpr (ALIGN_EPI) { if (wr == 0) PG8_BAR; }
;         if constexpr (!Epi::AFTER_DRAIN) { E(acc, cur, wr, wc, fr, fq); S.done(cur); }
.Lkexit2:
	s_and_b64 vcc, exec, s[14:15]
	s_cbranch_vccz .LBB0_774
	s_barrier

; #define PG8_STAGE(bufoff, gbase, voff) do { _Pragma("unroll") for (int _i = 0; _i < 2; ++_i) \
;         __builtin_amdgcn_global_load_lds((const unsigned*)((const char*)(gbase) + (voff)[_i]), (PG8_LAS unsigned*)(lds + (bufoff) + ldsw + _i * 8192), 16, 0, 0); } while (0)
; #define PG8_LDA(dst, b, h) do { _Pragma("unroll") for (int m = 0; m < 4; ++m) _Pragma("unroll") for (int k = 0; k < 2; ++k) dst[m][k] = *(const PG8_LAS bf16x8*)(lds + PG8_SA(b, h) + aoff + m * 2048 + k * 1024); } while (0)
; #define PG8_LDB(dst, b, h) do { _Pragma("unroll") for (int n = 0; n < 2; ++n) _Pragma("unroll") for (int k = 0; k < 2; ++k) dst[n][k] = *(const PG8_LAS bf16x8*)(lds + PG8_SB(b, h) + boff + n * 2048 + k * 1024); } while (0)
; #define PG8_MMA(ai, bj, At, Bt) do { __builtin_amdgcn_s_setprio(1); _Pragma("unroll") for (int m = 0; m < 4; ++m) _Pragma("unroll") for (int n = 0; n < 2; ++n) _Pragma("unroll") for (int k = 0; k < 2; ++k) \
;         acc[ai][bj][m][n] = __builtin_amdgcn_mfma_f32_16x16x32_bf16(Bt[n][k], At[m][k], acc[ai][bj][m][n], 0, 0, 0); __builtin_amdgcn_s_setprio(0); } while (0)
; #define PG8_WAIT_V(n) asm volatile("s_waitcnt vmcnt(" #n ")" ::: "memory")
; #define PG8_WAIT_L(n) asm volatile("s_waitcnt lgkmcnt(" #n ")" ::: "memory")
; #define PG8_BAR __builtin_amdgcn_s_barrier()
; #define PG8_SCHED __builtin_amdgcn_sched_barrier(0)
; template <class Epi, class Sched, bool ALIGN_EPI = false, bool SP2 = false>
; __device__ __forceinline__ void gemm_phase(PG8_LAS unsigned char* lds, const Gemm g, const Sched& S, const Epi& E) {
;     ...
;             PG8_LDB(B0, 0, 0); PG8_LDB(B1, 0, 1); PG8_SCHED; PG8_LDA(At, 0, 0); PG8_STAGE(PG8_SA(1, 1), a1 + hstep, voffA);
;             PG8_WAIT_V(8); PG8_WAIT_L(0); PG8_BAR; PG8_MMA(0, 0, At, B0); PG8_MMA(0, 1, At, B1); PG8_BAR; PG8_SCHED;
;             PG8_LDA(At, 0, 1); PG8_STAGE(PG8_SB(0, 0), b2, voffB); PG8_STAGE(PG8_SB(0, 1), b2 + hstep, voffB); PG8_STAGE(PG8_SA(0, 0), a2, voffA);
;             PG8_WAIT_V(8); PG8_WAIT_L(0); PG8_BAR; PG8_MMA(1, 0, At, B0); PG8_MMA(1, 1, At, B1); PG8_BAR; PG8_SCHED;
.LBB0_884:
	s_ashr_i32 s65, s64, 31
	s_lshl_b64 s[2:3], s[64:65], 19
	v_readlane_b32 s42, v254, 60
	v_readlane_b32 s43, v254, 61
	s_add_u32 s66, s42, s2
	s_addc_u32 s67, s43, s3
	s_and_b64 s[2:3], s[8:9], exec
	s_cselect_b32 s2, s67, s71
	s_cselect_b32 s3, s66, s70
	s_ashr_i32 s61, s60, 31
	s_lshl_b64 s[42:43], s[60:61], 19
	v_readlane_b32 s68, v254, 40
	v_readlane_b32 s69, v254, 41
	s_add_u32 s68, s68, s42
	s_addc_u32 s69, s69, s43
	s_and_b64 s[42:43], s[8:9], exec
	s_cselect_b32 s29, s69, s35
	s_cselect_b32 s61, s68, s34
	s_add_u32 s70, s70, 0x40080
	s_addc_u32 s71, s71, 0
	s_add_u32 s65, s34, 0x100
	s_addc_u32 s72, s35, 0
	s_mov_b32 s73, -2
	ds_read_b128 v[104:107], v221
	ds_read_b128 v[108:111], v221 offset:1024
	ds_read_b128 v[112:115], v221 offset:2048
	ds_read_b128 v[116:119], v221 offset:3072
	ds_read_b128 v[152:155], v222
	ds_read_b128 v[156:159], v222 offset:1024
	ds_read_b128 v[160:163], v222 offset:2048
	ds_read_b128 v[188:191], v222 offset:3072
	s_add_u32 s34, s70, 0xfffc0080
	s_addc_u32 s35, s71, -1
	s_cmp_eq_u32 s73, 12
	s_cselect_b32 s43, s2, s35
	s_cselect_b32 s42, s3, s34
	s_cselect_b32 s35, s29, s72
	s_cselect_b32 s34, s61, s65
	v_lshl_add_u64 v[86:87], s[70:71], 0, v[180:181]
	s_add_i32 m0, s45, 0xc000
	ds_read_b128 v[192:195], v223
	ds_read_b128 v[196:199], v223 offset:1024
	ds_read_b128 v[204:207], v223 offset:2048
	ds_read_b128 v[208:211], v223 offset:3072
	ds_read_b128 v[226:229], v223 offset:4096
	ds_read_b128 v[230:233], v223 offset:5120
	ds_read_b128 v[234:237], v223 offset:6144
	ds_read_b128 v[238:241], v223 offset:7168
	global_load_lds_dwordx4 v[86:87], off
	v_lshl_add_u64 v[86:87], s[70:71], 0, v[182:183]
	s_add_i32 m0, s45, 0xe000
	s_nop 0
	global_load_lds_dwordx4 v[86:87], off
	s_waitcnt vmcnt(8)
	s_waitcnt lgkmcnt(0)
	s_barrier
	s_setprio 1
	s_waitcnt lgkmcnt(0)
	v_mfma_f32_16x16x32_bf16 v[148:151], v[104:107], v[192:195], 0
	v_mfma_f32_16x16x32_bf16 v[62:65], v[112:115], v[192:195], 0
	v_mfma_f32_16x16x32_bf16 v[140:143], v[104:107], v[204:207], 0
	v_mfma_f32_16x16x32_bf16 v[54:57], v[112:115], v[204:207], 0
	v_mfma_f32_16x16x32_bf16 v[132:135], v[104:107], v[226:229], 0
	v_mfma_f32_16x16x32_bf16 v[46:49], v[112:115], v[226:229], 0
	v_mfma_f32_16x16x32_bf16 v[124:127], v[104:107], v[234:237], 0
	v_mfma_f32_16x16x32_bf16 v[38:41], v[112:115], v[234:237], 0
	v_mfma_f32_16x16x32_bf16 v[148:151], v[108:111], v[196:199], v[148:151]
	v_mfma_f32_16x16x32_bf16 v[62:65], v[116:119], v[196:199], v[62:65]
	v_mfma_f32_16x16x32_bf16 v[140:143], v[108:111], v[208:211], v[140:143]
	v_mfma_f32_16x16x32_bf16 v[54:57], v[116:119], v[208:211], v[54:57]
	v_mfma_f32_16x16x32_bf16 v[132:135], v[108:111], v[230:233], v[132:135]
	v_mfma_f32_16x16x32_bf16 v[46:49], v[116:119], v[230:233], v[46:49]
	v_mfma_f32_16x16x32_bf16 v[124:127], v[108:111], v[238:241], v[124:127]
	v_mfma_f32_16x16x32_bf16 v[38:41], v[116:119], v[238:241], v[38:41]
	s_setprio 0
	s_setprio 1
	v_mfma_f32_16x16x32_bf16 v[144:147], v[152:155], v[192:195], 0
	v_mfma_f32_16x16x32_bf16 v[58:61], v[160:163], v[192:195], 0
	v_mfma_f32_16x16x32_bf16 v[136:139], v[152:155], v[204:207], 0
	v_mfma_f32_16x16x32_bf16 v[50:53], v[160:163], v[204:207], 0
	v_mfma_f32_16x16x32_bf16 v[128:131], v[152:155], v[226:229], 0
	v_mfma_f32_16x16x32_bf16 v[42:45], v[160:163], v[226:229], 0
	v_mfma_f32_16x16x32_bf16 v[92:95], v[152:155], v[234:237], 0
	v_mfma_f32_16x16x32_bf16 v[34:37], v[160:163], v[234:237], 0
	v_mfma_f32_16x16x32_bf16 v[144:147], v[156:159], v[196:199], v[144:147]
	v_mfma_f32_16x16x32_bf16 v[58:61], v[188:191], v[196:199], v[58:61]
	v_mfma_f32_16x16x32_bf16 v[136:139], v[156:159], v[208:211], v[136:139]
	v_mfma_f32_16x16x32_bf16 v[50:53], v[188:191], v[208:211], v[50:53]
	v_mfma_f32_16x16x32_bf16 v[128:131], v[156:159], v[230:233], v[128:131]
	v_mfma_f32_16x16x32_bf16 v[42:45], v[188:191], v[230:233], v[42:45]
	v_mfma_f32_16x16x32_bf16 v[92:95], v[156:159], v[238:241], v[92:95]
	v_mfma_f32_16x16x32_bf16 v[34:37], v[188:191], v[238:241], v[34:37]
	s_setprio 0
	s_barrier
	s_add_i32 s74, s57, s44
	v_lshl_add_u64 v[200:201], s[34:35], 0, v[166:167]
	s_mov_b32 m0, s74
	ds_read_b128 v[96:99], v223 offset:16384
	ds_read_b128 v[192:195], v223 offset:17408
	ds_read_b128 v[196:199], v223 offset:18432
	ds_read_b128 v[204:207], v223 offset:19456
	ds_read_b128 v[208:211], v223 offset:20480
	ds_read_b128 v[226:229], v223 offset:21504
	ds_read_b128 v[230:233], v223 offset:22528
	ds_read_b128 v[234:237], v223 offset:23552
	global_load_lds_dwordx4 v[200:201], off
	s_add_i32 m0, s74, 0x2000
	s_add_u32 s74, s34, 0x40000
	v_lshl_add_u64 v[212:213], s[34:35], 0, v[170:171]
	s_addc_u32 s75, s35, 0
	s_add_i32 s79, s59, s44
	global_load_lds_dwordx4 v[212:213], off
	v_lshl_add_u64 v[86:87], s[74:75], 0, v[166:167]
	s_mov_b32 m0, s79
	v_lshl_add_u64 v[242:243], s[42:43], 0, v[164:165]
	global_load_lds_dwordx4 v[86:87], off
	v_lshl_add_u64 v[86:87], s[74:75], 0, v[170:171]
	s_add_i32 m0, s79, 0x2000
	v_lshl_add_u64 v[244:245], s[42:43], 0, v[168:169]
	global_load_lds_dwordx4 v[86:87], off
	s_mov_b32 m0, s45
	s_nop 0
	global_load_lds_dwordx4 v[242:243], off
	s_mov_b32 m0, s46
	s_nop 0
	global_load_lds_dwordx4 v[244:245], off
	s_waitcnt vmcnt(8)
	s_waitcnt lgkmcnt(0)
	s_barrier
; #define PG8_STAGE(bufoff, gbase, voff) do { _Pragma("unroll") for (int _i = 0; _i < 2; ++_i) \
;         __builtin_amdgcn_global_load_lds((const unsigned*)((const char*)(gbase) + (voff)[_i]), (PG8_LAS unsigned*)(lds + (bufoff) + ldsw + _i * 8192), 16, 0, 0); } while (0)
; #define PG8_LDA(dst, b, h) do { _Pragma("unroll") for (int m = 0; m < 4; ++m) _Pragma("unroll") for (int k = 0; k < 2; ++k) dst[m][k] = *(const PG8_LAS bf16x8*)(lds + PG8_SA(b, h) + aoff + m * 2048 + k * 1024); } while (0)
; #define PG8_LDB(dst, b, h) do { _Pragma("unroll") for (int n = 0; n < 2; ++n) _Pragma("unroll") for (int k = 0; k < 2; ++k) dst[n][k] = *(const PG8_LAS bf16x8*)(lds + PG8_SB(b, h) + boff + n * 2048 + k * 1024); } while (0)
; #define PG8_MMA(ai, bj, At, Bt) do { __builtin_amdgcn_s_setprio(1); _Pragma("unroll") for (int m = 0; m < 4; ++m) _Pragma("unroll") for (int n = 0; n < 2; ++n) _Pragma("unroll") for (int k = 0; k < 2; ++k) \
;         acc[ai][bj][m][n] = __builtin_amdgcn_mfma_f32_16x16x32_bf16(Bt[n][k], At[m][k], acc[ai][bj][m][n], 0, 0, 0); __builtin_amdgcn_s_setprio(0); } while (0)
; #define PG8_WAIT_V(n) asm volatile("s_waitcnt vmcnt(" #n ")" ::: "memory")
; #define PG8_WAIT_L(n) asm volatile("s_waitcnt lgkmcnt(" #n ")" ::: "memory")
; #define PG8_BAR __builtin_amdgcn_s_barrier()
; #define PG8_SCHED __builtin_amdgcn_sched_barrier(0)
; template <class Epi, class Sched, bool ALIGN_EPI = false, bool SP2 = false>
; __device__ __forceinline__ void gemm_phase(PG8_LAS unsigned char* lds, const Gemm g, const Sched& S, const Epi& E) {
;     ...
;             PG8_WAIT_V(8); PG8_WAIT_L(0); PG8_BAR; PG8_MMA(1, 0, At, B0); PG8_MMA(1, 1, At, B1); PG8_BAR; PG8_SCHED;
;             PG8_LDB(B0, 1, 0); PG8_LDB(B1, 1, 1); PG8_SCHED; PG8_LDA(At, 1, 0); PG8_STAGE(PG8_SA(0, 1), a2 + hstep, voffA);
;             PG8_WAIT_V(8); PG8_WAIT_L(0); PG8_BAR; PG8_MMA(0, 0, At, B0); PG8_MMA(0, 1, At, B1); PG8_BAR; PG8_SCHED;
	s_setprio 1
	s_waitcnt lgkmcnt(0)
	v_mfma_f32_16x16x32_bf16 v[120:123], v[104:107], v[96:99], 0
	v_mfma_f32_16x16x32_bf16 v[30:33], v[112:115], v[96:99], 0
	v_mfma_f32_16x16x32_bf16 v[86:89], v[104:107], v[196:199], 0
	v_mfma_f32_16x16x32_bf16 v[22:25], v[112:115], v[196:199], 0
	v_mfma_f32_16x16x32_bf16 v[78:81], v[104:107], v[208:211], 0
	v_mfma_f32_16x16x32_bf16 v[14:17], v[112:115], v[208:211], 0
	v_mfma_f32_16x16x32_bf16 v[74:77], v[104:107], v[230:233], 0
	v_mfma_f32_16x16x32_bf16 v[6:9], v[112:115], v[230:233], 0
	v_mfma_f32_16x16x32_bf16 v[120:123], v[108:111], v[192:195], v[120:123]
	v_mfma_f32_16x16x32_bf16 v[30:33], v[116:119], v[192:195], v[30:33]
	v_mfma_f32_16x16x32_bf16 v[86:89], v[108:111], v[204:207], v[86:89]
	v_mfma_f32_16x16x32_bf16 v[22:25], v[116:119], v[204:207], v[22:25]
	v_mfma_f32_16x16x32_bf16 v[78:81], v[108:111], v[226:229], v[78:81]
	v_mfma_f32_16x16x32_bf16 v[14:17], v[116:119], v[226:229], v[14:17]
	v_mfma_f32_16x16x32_bf16 v[74:77], v[108:111], v[234:237], v[74:77]
	v_mfma_f32_16x16x32_bf16 v[6:9], v[116:119], v[234:237], v[6:9]
	s_setprio 0
	s_setprio 1
	v_mfma_f32_16x16x32_bf16 v[100:103], v[152:155], v[96:99], 0
	v_mfma_f32_16x16x32_bf16 v[26:29], v[160:163], v[96:99], 0
	v_mfma_f32_16x16x32_bf16 v[82:85], v[152:155], v[196:199], 0
	v_mfma_f32_16x16x32_bf16 v[18:21], v[160:163], v[196:199], 0
	v_mfma_f32_16x16x32_bf16 v[70:73], v[152:155], v[208:211], 0
	v_mfma_f32_16x16x32_bf16 v[10:13], v[160:163], v[208:211], 0
	v_mfma_f32_16x16x32_bf16 v[66:69], v[152:155], v[230:233], 0
	v_mfma_f32_16x16x32_bf16 v[2:5], v[160:163], v[230:233], 0
	v_mfma_f32_16x16x32_bf16 v[100:103], v[156:159], v[192:195], v[100:103]
	v_mfma_f32_16x16x32_bf16 v[26:29], v[188:191], v[192:195], v[26:29]
	v_mfma_f32_16x16x32_bf16 v[82:85], v[156:159], v[204:207], v[82:85]
	v_mfma_f32_16x16x32_bf16 v[18:21], v[188:191], v[204:207], v[18:21]
	v_mfma_f32_16x16x32_bf16 v[70:73], v[156:159], v[226:229], v[70:73]
	v_mfma_f32_16x16x32_bf16 v[10:13], v[188:191], v[226:229], v[10:13]
	v_mfma_f32_16x16x32_bf16 v[66:69], v[156:159], v[234:237], v[66:69]
	v_mfma_f32_16x16x32_bf16 v[2:5], v[188:191], v[234:237], v[2:5]
	s_setprio 0
	s_barrier
	s_add_i32 s74, 0, 0x18000
	v_add_u32_e32 v90, s74, v203
	s_add_i32 s75, 0, 0x1c000
	ds_read_b128 v[104:107], v90
	ds_read_b128 v[108:111], v90 offset:1024
	ds_read_b128 v[112:115], v90 offset:2048
	ds_read_b128 v[116:119], v90 offset:3072
	v_add_u32_e32 v90, s75, v203
	ds_read_b128 v[152:155], v90
	ds_read_b128 v[156:159], v90 offset:1024
	ds_read_b128 v[160:163], v90 offset:2048
	ds_read_b128 v[188:191], v90 offset:3072
	s_add_u32 s42, s42, 0x40000
	s_addc_u32 s43, s43, 0
	s_mov_b32 m0, s47
	v_lshl_add_u64 v[90:91], s[42:43], 0, v[164:165]
	ds_read_b128 v[96:99], v223 offset:32768
	ds_read_b128 v[192:195], v223 offset:33792
	ds_read_b128 v[196:199], v223 offset:34816
	ds_read_b128 v[204:207], v223 offset:35840
	ds_read_b128 v[208:211], v223 offset:36864
	ds_read_b128 v[226:229], v223 offset:37888
	ds_read_b128 v[230:233], v223 offset:38912
	ds_read_b128 v[234:237], v223 offset:39936
	global_load_lds_dwordx4 v[90:91], off
	v_lshl_add_u64 v[90:91], s[42:43], 0, v[168:169]
	s_mov_b32 m0, s48
	s_nop 0
	global_load_lds_dwordx4 v[90:91], off
	s_waitcnt vmcnt(8)
	s_waitcnt lgkmcnt(0)
	s_barrier
	s_setprio 1
	s_waitcnt lgkmcnt(0)
	v_mfma_f32_16x16x32_bf16 v[148:151], v[104:107], v[96:99], v[148:151]
	v_mfma_f32_16x16x32_bf16 v[62:65], v[112:115], v[96:99], v[62:65]
	v_mfma_f32_16x16x32_bf16 v[140:143], v[104:107], v[196:199], v[140:143]
	v_mfma_f32_16x16x32_bf16 v[54:57], v[112:115], v[196:199], v[54:57]
	v_mfma_f32_16x16x32_bf16 v[132:135], v[104:107], v[208:211], v[132:135]
	v_mfma_f32_16x16x32_bf16 v[46:49], v[112:115], v[208:211], v[46:49]
	v_mfma_f32_16x16x32_bf16 v[124:127], v[104:107], v[230:233], v[124:127]
	v_mfma_f32_16x16x32_bf16 v[38:41], v[112:115], v[230:233], v[38:41]
	v_mfma_f32_16x16x32_bf16 v[148:151], v[108:111], v[192:195], v[148:151]
	v_mfma_f32_16x16x32_bf16 v[62:65], v[116:119], v[192:195], v[62:65]
	v_mfma_f32_16x16x32_bf16 v[140:143], v[108:111], v[204:207], v[140:143]
	v_mfma_f32_16x16x32_bf16 v[54:57], v[116:119], v[204:207], v[54:57]
	v_mfma_f32_16x16x32_bf16 v[132:135], v[108:111], v[226:229], v[132:135]
	v_mfma_f32_16x16x32_bf16 v[46:49], v[116:119], v[226:229], v[46:49]
	v_mfma_f32_16x16x32_bf16 v[124:127], v[108:111], v[234:237], v[124:127]
	v_mfma_f32_16x16x32_bf16 v[38:41], v[116:119], v[234:237], v[38:41]
	s_setprio 0
	s_setprio 1
	v_mfma_f32_16x16x32_bf16 v[144:147], v[152:155], v[96:99], v[144:147]
	v_mfma_f32_16x16x32_bf16 v[58:61], v[160:163], v[96:99], v[58:61]
	v_mfma_f32_16x16x32_bf16 v[96:99], v[152:155], v[196:199], v[136:139]
	v_mfma_f32_16x16x32_bf16 v[136:139], v[156:159], v[204:207], v[96:99]
	v_mfma_f32_16x16x32_bf16 v[50:53], v[160:163], v[196:199], v[50:53]
	v_mfma_f32_16x16x32_bf16 v[96:99], v[152:155], v[208:211], v[128:131]
	v_mfma_f32_16x16x32_bf16 v[42:45], v[160:163], v[208:211], v[42:45]
	v_mfma_f32_16x16x32_bf16 v[90:93], v[152:155], v[230:233], v[92:95]
	v_mfma_f32_16x16x32_bf16 v[34:37], v[160:163], v[230:233], v[34:37]
	v_mfma_f32_16x16x32_bf16 v[144:147], v[156:159], v[192:195], v[144:147]
	v_mfma_f32_16x16x32_bf16 v[58:61], v[188:191], v[192:195], v[58:61]
	v_mfma_f32_16x16x32_bf16 v[50:53], v[188:191], v[204:207], v[50:53]
	v_mfma_f32_16x16x32_bf16 v[128:131], v[156:159], v[226:229], v[96:99]
	v_mfma_f32_16x16x32_bf16 v[42:45], v[188:191], v[226:229], v[42:45]
	v_mfma_f32_16x16x32_bf16 v[94:97], v[156:159], v[234:237], v[90:93]
	v_mfma_f32_16x16x32_bf16 v[34:37], v[188:191], v[234:237], v[34:37]
	s_setprio 0
	s_barrier
; #define PG8_STAGE(bufoff, gbase, voff) do { _Pragma("unroll") for (int _i = 0; _i < 2; ++_i) \
;         __builtin_amdgcn_global_load_lds((const unsigned*)((const char*)(gbase) + (voff)[_i]), (PG8_LAS unsigned*)(lds + (bufoff) + ldsw + _i * 8192), 16, 0, 0); } while (0)
; #define PG8_LDA(dst, b, h) do { _Pragma("unroll") for (int m = 0; m < 4; ++m) _Pragma("unroll") for (int k = 0; k < 2; ++k) dst[m][k] = *(const PG8_LAS bf16x8*)(lds + PG8_SA(b, h) + aoff + m * 2048 + k * 1024); } while (0)
; #define PG8_MMA(ai, bj, At, Bt) do { __builtin_amdgcn_s_setprio(1); _Pragma("unroll") for (int m = 0; m < 4; ++m) _Pragma("unroll") for (int n = 0; n < 2; ++n) _Pragma("unroll") for (int k = 0; k < 2; ++k) \
;         acc[ai][bj][m][n] = __builtin_amdgcn_mfma_f32_16x16x32_bf16(Bt[n][k], At[m][k], acc[ai][bj][m][n], 0, 0, 0); __builtin_amdgcn_s_setprio(0); } while (0)
; #define PG8_WAIT_V(n) asm volatile("s_waitcnt vmcnt(" #n ")" ::: "memory")
; #define PG8_WAIT_L(n) asm volatile("s_waitcnt lgkmcnt(" #n ")" ::: "memory")
; #define PG8_BAR __builtin_amdgcn_s_barrier()
; #define PG8_SCHED __builtin_amdgcn_sched_barrier(0)
; template <class Epi, class Sched, bool ALIGN_EPI = false, bool SP2 = false>
; __device__ __forceinline__ void gemm_phase(PG8_LAS unsigned char* lds, const Gemm g, const Sched& S, const Epi& E) {
;     ...
;         for (int t = 0; t < nt; t += 2) {
;     ...
;             PG8_LDA(At, 1, 1); PG8_STAGE(PG8_SB(1, 0), b3, voffB); PG8_STAGE(PG8_SB(1, 1), b3 + hstep, voffB); PG8_STAGE(PG8_SA(1, 0), a3, voffA);
;             PG8_WAIT_V(8); PG8_WAIT_L(0); PG8_BAR; PG8_MMA(1, 0, At, B0); PG8_MMA(1, 1, At, B1); PG8_BAR; PG8_SCHED;
	s_add_i32 s42, s74, s44
	v_lshl_add_u64 v[90:91], v[200:201], 0, s[22:23]
	s_mov_b32 m0, s42
	ds_read_b128 v[192:195], v223 offset:49152
	ds_read_b128 v[196:199], v223 offset:50176
	ds_read_b128 v[204:207], v223 offset:51200
	ds_read_b128 v[208:211], v223 offset:52224
	ds_read_b128 v[226:229], v223 offset:53248
	ds_read_b128 v[230:233], v223 offset:54272
	ds_read_b128 v[234:237], v223 offset:55296
	ds_read_b128 v[238:241], v223 offset:56320
	global_load_lds_dwordx4 v[90:91], off
	s_add_i32 m0, s42, 0x2000
	s_add_u32 s34, s34, 0x40080
	v_lshl_add_u64 v[90:91], v[212:213], 0, s[22:23]
	s_addc_u32 s35, s35, 0
	s_add_i32 s42, s75, s44
	global_load_lds_dwordx4 v[90:91], off
	v_lshl_add_u64 v[90:91], s[34:35], 0, v[166:167]
	s_mov_b32 m0, s42
	s_nop 0
	global_load_lds_dwordx4 v[90:91], off
	v_lshl_add_u64 v[90:91], s[34:35], 0, v[170:171]
	s_add_i32 m0, s42, 0x2000
	s_nop 0
	global_load_lds_dwordx4 v[90:91], off
	v_lshl_add_u64 v[90:91], v[242:243], 0, s[22:23]
	s_mov_b32 m0, s49
	s_nop 0
	global_load_lds_dwordx4 v[90:91], off
	v_lshl_add_u64 v[90:91], v[244:245], 0, s[22:23]
	s_mov_b32 m0, s50
	s_nop 0
	global_load_lds_dwordx4 v[90:91], off
	s_waitcnt vmcnt(8)
	s_waitcnt lgkmcnt(0)
	s_barrier
	s_setprio 1
	s_waitcnt lgkmcnt(0)
	v_mfma_f32_16x16x32_bf16 v[90:93], v[104:107], v[192:195], v[120:123]
	v_mfma_f32_16x16x32_bf16 v[30:33], v[112:115], v[192:195], v[30:33]
	v_mfma_f32_16x16x32_bf16 v[86:89], v[104:107], v[204:207], v[86:89]
	v_mfma_f32_16x16x32_bf16 v[22:25], v[112:115], v[204:207], v[22:25]
	v_mfma_f32_16x16x32_bf16 v[78:81], v[104:107], v[226:229], v[78:81]
	v_mfma_f32_16x16x32_bf16 v[14:17], v[112:115], v[226:229], v[14:17]
	v_mfma_f32_16x16x32_bf16 v[74:77], v[104:107], v[234:237], v[74:77]
	v_mfma_f32_16x16x32_bf16 v[6:9], v[112:115], v[234:237], v[6:9]
	v_mfma_f32_16x16x32_bf16 v[120:123], v[108:111], v[196:199], v[90:93]
	v_mfma_f32_16x16x32_bf16 v[30:33], v[116:119], v[196:199], v[30:33]
	v_mfma_f32_16x16x32_bf16 v[88:91], v[108:111], v[208:211], v[86:89]
	v_mfma_f32_16x16x32_bf16 v[22:25], v[116:119], v[208:211], v[22:25]
	v_mfma_f32_16x16x32_bf16 v[78:81], v[108:111], v[230:233], v[78:81]
	v_mfma_f32_16x16x32_bf16 v[14:17], v[116:119], v[230:233], v[14:17]
	v_mfma_f32_16x16x32_bf16 v[74:77], v[108:111], v[238:241], v[74:77]
	v_mfma_f32_16x16x32_bf16 v[6:9], v[116:119], v[238:241], v[6:9]
	s_setprio 0
	s_setprio 1
	v_mfma_f32_16x16x32_bf16 v[98:101], v[152:155], v[192:195], v[100:103]
	v_mfma_f32_16x16x32_bf16 v[26:29], v[160:163], v[192:195], v[26:29]
	v_mfma_f32_16x16x32_bf16 v[82:85], v[152:155], v[204:207], v[82:85]
	v_mfma_f32_16x16x32_bf16 v[18:21], v[160:163], v[204:207], v[18:21]
	v_mfma_f32_16x16x32_bf16 v[70:73], v[152:155], v[226:229], v[70:73]
	v_mfma_f32_16x16x32_bf16 v[10:13], v[160:163], v[226:229], v[10:13]
	v_mfma_f32_16x16x32_bf16 v[66:69], v[152:155], v[234:237], v[66:69]
	v_mfma_f32_16x16x32_bf16 v[2:5], v[160:163], v[234:237], v[2:5]
	v_mfma_f32_16x16x32_bf16 v[100:103], v[156:159], v[196:199], v[98:101]
	v_mfma_f32_16x16x32_bf16 v[26:29], v[188:191], v[196:199], v[26:29]
	v_mfma_f32_16x16x32_bf16 v[82:85], v[156:159], v[208:211], v[82:85]
	v_mfma_f32_16x16x32_bf16 v[18:21], v[188:191], v[208:211], v[18:21]
	v_mfma_f32_16x16x32_bf16 v[70:73], v[156:159], v[230:233], v[70:73]
	v_mfma_f32_16x16x32_bf16 v[10:13], v[188:191], v[230:233], v[10:13]
	v_mfma_f32_16x16x32_bf16 v[66:69], v[156:159], v[238:241], v[66:69]
	v_mfma_f32_16x16x32_bf16 v[2:5], v[188:191], v[238:241], v[2:5]
	s_setprio 0
	s_barrier
	s_add_i32 s73, s73, 2
	s_add_u32 s70, s70, 0x100
	s_addc_u32 s71, s71, 0
	s_add_u32 s65, s65, 0x100
	s_addc_u32 s72, s72, 0
	s_cmp_gt_u32 s73, 13
	s_cbranch_scc0 .LBB0_885
	s_branch .Lkexit3

; #define PG8_BAR __builtin_amdgcn_s_barrier()
; template <class Epi, class Sched, bool ALIGN_EPI = false, bool SP2 = false>
; __device__ __forceinline__ void gemm_phase(PG8_LAS unsigned char* lds, const Gemm g, const Sched& S, const Epi& E) {
;     ...
;         if constexpr (ALIGN_EPI) { if (wr == 0) PG8_BAR; }
.Lkexit3:
	s_and_b64 vcc, exec, s[24:25]
	s_cbranch_vccz .LBB0_888
	s_barrier

; #define PG8_STAGE(bufoff, gbase, voff) do { _Pragma("unroll") for (int _i = 0; _i < 2; ++_i) \
;         __builtin_amdgcn_global_load_lds((const unsigned*)((const char*)(gbase) + (voff)[_i]), (PG8_LAS unsigned*)(lds + (bufoff) + ldsw + _i * 8192), 16, 0, 0); } while (0)
; #define PG8_LDA(dst, b, h) do { _Pragma("unroll") for (int m = 0; m < 4; ++m) _Pragma("unroll") for (int k = 0; k < 2; ++k) dst[m][k] = *(const PG8_LAS bf16x8*)(lds + PG8_SA(b, h) + aoff + m * 2048 + k * 1024); } while (0)
; #define PG8_LDB(dst, b, h) do { _Pragma("unroll") for (int n = 0; n < 2; ++n) _Pragma("unroll") for (int k = 0; k < 2; ++k) dst[n][k] = *(const PG8_LAS bf16x8*)(lds + PG8_SB(b, h) + boff + n * 2048 + k * 1024); } while (0)
; #define PG8_MMA(ai, bj, At, Bt) do { __builtin_amdgcn_s_setprio(1); _Pragma("unroll") for (int m = 0; m < 4; ++m) _Pragma("unroll") for (int n = 0; n < 2; ++n) _Pragma("unroll") for (int k = 0; k < 2; ++k) \
;         acc[ai][bj][m][n] = __builtin_amdgcn_mfma_f32_16x16x32_bf16(Bt[n][k], At[m][k], acc[ai][bj][m][n], 0, 0, 0); __builtin_amdgcn_s_setprio(0); } while (0)
; #define PG8_WAIT_V(n) asm volatile("s_waitcnt vmcnt(" #n ")" ::: "memory")
; #define PG8_WAIT_L(n) asm volatile("s_waitcnt lgkmcnt(" #n ")" ::: "memory")
; #define PG8_BAR __builtin_amdgcn_s_barrier()
; #define PG8_SCHED __builtin_amdgcn_sched_barrier(0)
; template <class Epi, class Sched, bool ALIGN_EPI = false, bool SP2 = false>
; __device__ __forceinline__ void gemm_phase(PG8_LAS unsigned char* lds, const Gemm g, const Sched& S, const Epi& E) {
;     ...
;             PG8_LDB(B0, 0, 0); PG8_LDB(B1, 0, 1); PG8_SCHED; PG8_LDA(At, 0, 0); PG8_STAGE(PG8_SA(1, 1), a1 + hstep, voffA);
;             PG8_WAIT_V(8); PG8_WAIT_L(0); PG8_BAR; PG8_MMA(0, 0, At, B0); PG8_MMA(0, 1, At, B1); PG8_BAR; PG8_SCHED;
;             PG8_LDA(At, 0, 1); PG8_STAGE(PG8_SB(0, 0), b2, voffB); PG8_STAGE(PG8_SB(0, 1), b2 + hstep, voffB); PG8_STAGE(PG8_SA(0, 0), a2, voffA);
;             PG8_WAIT_V(8); PG8_WAIT_L(0); PG8_BAR; PG8_MMA(1, 0, At, B0); PG8_MMA(1, 1, At, B1); PG8_BAR; PG8_SCHED;
.LBB0_1200:
	s_add_u32 s2, s20, 0x100
	s_addc_u32 s3, s21, 0
	v_lshl_add_u64 v[146:147], s[12:13], 0, v[94:95]
	v_lshl_add_u64 v[148:149], s[12:13], 0, v[96:97]
	s_mov_b32 s46, -2
	s_mov_b64 s[20:21], 0
	v_add_u32_e32 v164, s41, v150
	v_add_u32_e32 v180, s42, v150
	s_add_u32 s22, s12, s20
	ds_read_b128 v[152:155], v164
	ds_read_b128 v[156:159], v164 offset:1024
	ds_read_b128 v[160:163], v164 offset:2048
	ds_read_b128 v[164:167], v164 offset:3072
	ds_read_b128 v[168:171], v180
	ds_read_b128 v[172:175], v180 offset:1024
	ds_read_b128 v[176:179], v180 offset:2048
	ds_read_b128 v[180:183], v180 offset:3072
	s_addc_u32 s23, s13, s21
	s_add_u32 s22, s22, 0x100
	s_addc_u32 s23, s23, 0
	s_add_u32 s47, s2, s20
	s_addc_u32 s48, s3, s21
	s_cmpk_eq_i32 s20, 0x1500
	s_cselect_b32 s25, s19, s23
	s_cselect_b32 s24, s18, s22
	s_cselect_b32 s23, s7, s48
	s_cselect_b32 s22, s6, s47
	v_lshl_add_u64 v[200:201], v[146:147], 0, s[20:21]
	s_add_i32 m0, s33, 0xc000
	ds_read_b128 v[184:187], v151
	ds_read_b128 v[188:191], v151 offset:1024
	ds_read_b128 v[192:195], v151 offset:2048
	ds_read_b128 v[196:199], v151 offset:3072
	ds_read_b128 v[208:211], v151 offset:4096
	ds_read_b128 v[212:215], v151 offset:5120
	ds_read_b128 v[216:219], v151 offset:6144
	ds_read_b128 v[220:223], v151 offset:7168
	global_load_lds_dwordx4 v[200:201], off
	v_lshl_add_u64 v[200:201], v[148:149], 0, s[20:21]
	s_add_i32 m0, s33, 0xe000
	s_nop 0
	global_load_lds_dwordx4 v[200:201], off
	s_waitcnt vmcnt(8)
	s_waitcnt lgkmcnt(0)
	s_barrier
	s_setprio 1
	s_waitcnt lgkmcnt(0)
	v_mfma_f32_16x16x32_bf16 v[142:145], v[152:155], v[184:187], 0
	v_mfma_f32_16x16x32_bf16 v[138:141], v[160:163], v[184:187], 0
	v_mfma_f32_16x16x32_bf16 v[122:125], v[152:155], v[192:195], 0
	v_mfma_f32_16x16x32_bf16 v[118:121], v[160:163], v[192:195], 0
	v_mfma_f32_16x16x32_bf16 v[106:109], v[152:155], v[208:211], 0
	v_mfma_f32_16x16x32_bf16 v[102:105], v[160:163], v[208:211], 0
	v_mfma_f32_16x16x32_bf16 v[86:89], v[152:155], v[216:219], 0
	v_mfma_f32_16x16x32_bf16 v[82:85], v[160:163], v[216:219], 0
	v_mfma_f32_16x16x32_bf16 v[142:145], v[156:159], v[188:191], v[142:145]
	v_mfma_f32_16x16x32_bf16 v[138:141], v[164:167], v[188:191], v[138:141]
	v_mfma_f32_16x16x32_bf16 v[122:125], v[156:159], v[196:199], v[122:125]
	v_mfma_f32_16x16x32_bf16 v[118:121], v[164:167], v[196:199], v[118:121]
	v_mfma_f32_16x16x32_bf16 v[106:109], v[156:159], v[212:215], v[106:109]
	v_mfma_f32_16x16x32_bf16 v[102:105], v[164:167], v[212:215], v[102:105]
	v_mfma_f32_16x16x32_bf16 v[86:89], v[156:159], v[220:223], v[86:89]
	v_mfma_f32_16x16x32_bf16 v[82:85], v[164:167], v[220:223], v[82:85]
	s_setprio 0
	s_setprio 1
	v_mfma_f32_16x16x32_bf16 v[130:133], v[168:171], v[184:187], 0
	v_mfma_f32_16x16x32_bf16 v[126:129], v[176:179], v[184:187], 0
	v_mfma_f32_16x16x32_bf16 v[114:117], v[168:171], v[192:195], 0
	v_mfma_f32_16x16x32_bf16 v[110:113], v[176:179], v[192:195], 0
	v_mfma_f32_16x16x32_bf16 v[98:101], v[168:171], v[208:211], 0
	v_mfma_f32_16x16x32_bf16 v[90:93], v[176:179], v[208:211], 0
	v_mfma_f32_16x16x32_bf16 v[78:81], v[168:171], v[216:219], 0
	v_mfma_f32_16x16x32_bf16 v[74:77], v[176:179], v[216:219], 0
	v_mfma_f32_16x16x32_bf16 v[130:133], v[172:175], v[188:191], v[130:133]
	v_mfma_f32_16x16x32_bf16 v[126:129], v[180:183], v[188:191], v[126:129]
	v_mfma_f32_16x16x32_bf16 v[114:117], v[172:175], v[196:199], v[114:117]
	v_mfma_f32_16x16x32_bf16 v[110:113], v[180:183], v[196:199], v[110:113]
	v_mfma_f32_16x16x32_bf16 v[98:101], v[172:175], v[212:215], v[98:101]
	v_mfma_f32_16x16x32_bf16 v[90:93], v[180:183], v[212:215], v[90:93]
	v_mfma_f32_16x16x32_bf16 v[78:81], v[172:175], v[220:223], v[78:81]
	v_mfma_f32_16x16x32_bf16 v[74:77], v[180:183], v[220:223], v[74:77]
	s_setprio 0
	s_barrier
	s_add_i32 s47, s41, s31
	v_lshl_add_u64 v[200:201], s[22:23], 0, v[12:13]
	s_mov_b32 m0, s47
	ds_read_b128 v[184:187], v151 offset:16384
	ds_read_b128 v[188:191], v151 offset:17408
	ds_read_b128 v[192:195], v151 offset:18432
	ds_read_b128 v[196:199], v151 offset:19456
	ds_read_b128 v[208:211], v151 offset:20480
	ds_read_b128 v[212:215], v151 offset:21504
	ds_read_b128 v[216:219], v151 offset:22528
	ds_read_b128 v[220:223], v151 offset:23552
	global_load_lds_dwordx4 v[200:201], off
	s_add_i32 m0, s47, 0x2000
	s_add_u32 s48, s22, 0xb0000
	v_lshl_add_u64 v[204:205], s[22:23], 0, v[56:57]
	s_addc_u32 s49, s23, 0
	s_add_i32 s47, s42, s31
	global_load_lds_dwordx4 v[204:205], off
	v_lshl_add_u64 v[224:225], s[48:49], 0, v[12:13]
	s_mov_b32 m0, s47
	v_lshl_add_u64 v[226:227], s[24:25], 0, v[54:55]
	global_load_lds_dwordx4 v[224:225], off
	v_lshl_add_u64 v[224:225], s[48:49], 0, v[56:57]
	s_add_i32 m0, s47, 0x2000
	s_nop 0
	global_load_lds_dwordx4 v[224:225], off
	v_lshl_add_u64 v[224:225], s[24:25], 0, v[10:11]
	s_mov_b32 m0, s33
	s_nop 0
	global_load_lds_dwordx4 v[224:225], off
	s_mov_b32 m0, s34
	s_nop 0
	global_load_lds_dwordx4 v[226:227], off
	s_waitcnt vmcnt(8)
	s_waitcnt lgkmcnt(0)
	s_barrier
; #define PG8_STAGE(bufoff, gbase, voff) do { _Pragma("unroll") for (int _i = 0; _i < 2; ++_i) \
;         __builtin_amdgcn_global_load_lds((const unsigned*)((const char*)(gbase) + (voff)[_i]), (PG8_LAS unsigned*)(lds + (bufoff) + ldsw + _i * 8192), 16, 0, 0); } while (0)
; #define PG8_LDA(dst, b, h) do { _Pragma("unroll") for (int m = 0; m < 4; ++m) _Pragma("unroll") for (int k = 0; k < 2; ++k) dst[m][k] = *(const PG8_LAS bf16x8*)(lds + PG8_SA(b, h) + aoff + m * 2048 + k * 1024); } while (0)
; #define PG8_LDB(dst, b, h) do { _Pragma("unroll") for (int n = 0; n < 2; ++n) _Pragma("unroll") for (int k = 0; k < 2; ++k) dst[n][k] = *(const PG8_LAS bf16x8*)(lds + PG8_SB(b, h) + boff + n * 2048 + k * 1024); } while (0)
; #define PG8_MMA(ai, bj, At, Bt) do { __builtin_amdgcn_s_setprio(1); _Pragma("unroll") for (int m = 0; m < 4; ++m) _Pragma("unroll") for (int n = 0; n < 2; ++n) _Pragma("unroll") for (int k = 0; k < 2; ++k) \
;         acc[ai][bj][m][n] = __builtin_amdgcn_mfma_f32_16x16x32_bf16(Bt[n][k], At[m][k], acc[ai][bj][m][n], 0, 0, 0); __builtin_amdgcn_s_setprio(0); } while (0)
; #define PG8_WAIT_V(n) asm volatile("s_waitcnt vmcnt(" #n ")" ::: "memory")
; #define PG8_WAIT_L(n) asm volatile("s_waitcnt lgkmcnt(" #n ")" ::: "memory")
; #define PG8_BAR __builtin_amdgcn_s_barrier()
; #define PG8_SCHED __builtin_amdgcn_sched_barrier(0)
; template <class Epi, class Sched, bool ALIGN_EPI = false, bool SP2 = false>
; __device__ __forceinline__ void gemm_phase(PG8_LAS unsigned char* lds, const Gemm g, const Sched& S, const Epi& E) {
;     ...
;             PG8_WAIT_V(8); PG8_WAIT_L(0); PG8_BAR; PG8_MMA(1, 0, At, B0); PG8_MMA(1, 1, At, B1); PG8_BAR; PG8_SCHED;
;             PG8_LDB(B0, 1, 0); PG8_LDB(B1, 1, 1); PG8_SCHED; PG8_LDA(At, 1, 0); PG8_STAGE(PG8_SA(0, 1), a2 + hstep, voffA);
;             PG8_WAIT_V(8); PG8_WAIT_L(0); PG8_BAR; PG8_MMA(0, 0, At, B0); PG8_MMA(0, 1, At, B1); PG8_BAR; PG8_SCHED;
;             PG8_LDA(At, 1, 1); PG8_STAGE(PG8_SB(1, 0), b3, voffB); PG8_STAGE(PG8_SB(1, 1), b3 + hstep, voffB); PG8_STAGE(PG8_SA(1, 0), a3, voffA);
	s_setprio 1
	s_waitcnt lgkmcnt(0)
	v_mfma_f32_16x16x32_bf16 v[70:73], v[152:155], v[184:187], 0
	v_mfma_f32_16x16x32_bf16 v[66:69], v[160:163], v[184:187], 0
	v_mfma_f32_16x16x32_bf16 v[50:53], v[152:155], v[192:195], 0
	v_mfma_f32_16x16x32_bf16 v[46:49], v[160:163], v[192:195], 0
	v_mfma_f32_16x16x32_bf16 v[34:37], v[152:155], v[208:211], 0
	v_mfma_f32_16x16x32_bf16 v[30:33], v[160:163], v[208:211], 0
	v_mfma_f32_16x16x32_bf16 v[18:21], v[152:155], v[216:219], 0
	v_mfma_f32_16x16x32_bf16 v[14:17], v[160:163], v[216:219], 0
	v_mfma_f32_16x16x32_bf16 v[70:73], v[156:159], v[188:191], v[70:73]
	v_mfma_f32_16x16x32_bf16 v[66:69], v[164:167], v[188:191], v[66:69]
	v_mfma_f32_16x16x32_bf16 v[50:53], v[156:159], v[196:199], v[50:53]
	v_mfma_f32_16x16x32_bf16 v[46:49], v[164:167], v[196:199], v[46:49]
	v_mfma_f32_16x16x32_bf16 v[34:37], v[156:159], v[212:215], v[34:37]
	v_mfma_f32_16x16x32_bf16 v[30:33], v[164:167], v[212:215], v[30:33]
	v_mfma_f32_16x16x32_bf16 v[18:21], v[156:159], v[220:223], v[18:21]
	v_mfma_f32_16x16x32_bf16 v[14:17], v[164:167], v[220:223], v[14:17]
	s_setprio 0
	s_setprio 1
	v_mfma_f32_16x16x32_bf16 v[62:65], v[168:171], v[184:187], 0
	v_mfma_f32_16x16x32_bf16 v[58:61], v[176:179], v[184:187], 0
	v_mfma_f32_16x16x32_bf16 v[42:45], v[168:171], v[192:195], 0
	v_mfma_f32_16x16x32_bf16 v[38:41], v[176:179], v[192:195], 0
	v_mfma_f32_16x16x32_bf16 v[26:29], v[168:171], v[208:211], 0
	v_mfma_f32_16x16x32_bf16 v[22:25], v[176:179], v[208:211], 0
	v_mfma_f32_16x16x32_bf16 v[6:9], v[168:171], v[216:219], 0
	v_mfma_f32_16x16x32_bf16 v[2:5], v[176:179], v[216:219], 0
	v_mfma_f32_16x16x32_bf16 v[62:65], v[172:175], v[188:191], v[62:65]
	v_mfma_f32_16x16x32_bf16 v[58:61], v[180:183], v[188:191], v[58:61]
	v_mfma_f32_16x16x32_bf16 v[42:45], v[172:175], v[196:199], v[42:45]
	v_mfma_f32_16x16x32_bf16 v[38:41], v[180:183], v[196:199], v[38:41]
	v_mfma_f32_16x16x32_bf16 v[26:29], v[172:175], v[212:215], v[26:29]
	v_mfma_f32_16x16x32_bf16 v[22:25], v[180:183], v[212:215], v[22:25]
	v_mfma_f32_16x16x32_bf16 v[6:9], v[172:175], v[220:223], v[6:9]
	v_mfma_f32_16x16x32_bf16 v[2:5], v[180:183], v[220:223], v[2:5]
	s_setprio 0
	s_barrier
	s_add_i32 s47, 0, 0x18000
	s_add_i32 s48, 0, 0x1c000
	v_add_u32_e32 v164, s47, v150
	v_add_u32_e32 v180, s48, v150
	ds_read_b128 v[152:155], v164
	ds_read_b128 v[156:159], v164 offset:1024
	ds_read_b128 v[160:163], v164 offset:2048
	ds_read_b128 v[164:167], v164 offset:3072
	ds_read_b128 v[168:171], v180
	ds_read_b128 v[172:175], v180 offset:1024
	ds_read_b128 v[176:179], v180 offset:2048
	ds_read_b128 v[180:183], v180 offset:3072
	s_add_u32 s24, s24, 0xb0000
	s_addc_u32 s25, s25, 0
	s_mov_b32 m0, s35
	v_lshl_add_u64 v[228:229], s[24:25], 0, v[10:11]
	ds_read_b128 v[184:187], v151 offset:32768
	ds_read_b128 v[188:191], v151 offset:33792
	ds_read_b128 v[192:195], v151 offset:34816
	ds_read_b128 v[196:199], v151 offset:35840
	ds_read_b128 v[208:211], v151 offset:36864
	ds_read_b128 v[212:215], v151 offset:37888
	ds_read_b128 v[216:219], v151 offset:38912
	ds_read_b128 v[220:223], v151 offset:39936
	global_load_lds_dwordx4 v[228:229], off
	v_lshl_add_u64 v[228:229], s[24:25], 0, v[54:55]
	s_mov_b32 m0, s36
	s_nop 0
	global_load_lds_dwordx4 v[228:229], off
	s_waitcnt vmcnt(8)
	s_waitcnt lgkmcnt(0)
	s_barrier
	s_setprio 1
	s_waitcnt lgkmcnt(0)
	v_mfma_f32_16x16x32_bf16 v[142:145], v[152:155], v[184:187], v[142:145]
	v_mfma_f32_16x16x32_bf16 v[138:141], v[160:163], v[184:187], v[138:141]
	v_mfma_f32_16x16x32_bf16 v[122:125], v[152:155], v[192:195], v[122:125]
	v_mfma_f32_16x16x32_bf16 v[118:121], v[160:163], v[192:195], v[118:121]
	v_mfma_f32_16x16x32_bf16 v[106:109], v[152:155], v[208:211], v[106:109]
	v_mfma_f32_16x16x32_bf16 v[102:105], v[160:163], v[208:211], v[102:105]
	v_mfma_f32_16x16x32_bf16 v[86:89], v[152:155], v[216:219], v[86:89]
	v_mfma_f32_16x16x32_bf16 v[82:85], v[160:163], v[216:219], v[82:85]
	v_mfma_f32_16x16x32_bf16 v[142:145], v[156:159], v[188:191], v[142:145]
	v_mfma_f32_16x16x32_bf16 v[138:141], v[164:167], v[188:191], v[138:141]
	v_mfma_f32_16x16x32_bf16 v[122:125], v[156:159], v[196:199], v[122:125]
	v_mfma_f32_16x16x32_bf16 v[118:121], v[164:167], v[196:199], v[118:121]
	v_mfma_f32_16x16x32_bf16 v[106:109], v[156:159], v[212:215], v[106:109]
	v_mfma_f32_16x16x32_bf16 v[102:105], v[164:167], v[212:215], v[102:105]
	v_mfma_f32_16x16x32_bf16 v[86:89], v[156:159], v[220:223], v[86:89]
	v_mfma_f32_16x16x32_bf16 v[82:85], v[164:167], v[220:223], v[82:85]
	s_setprio 0
	s_setprio 1
	v_mfma_f32_16x16x32_bf16 v[130:133], v[168:171], v[184:187], v[130:133]
	v_mfma_f32_16x16x32_bf16 v[126:129], v[176:179], v[184:187], v[126:129]
	v_mfma_f32_16x16x32_bf16 v[114:117], v[168:171], v[192:195], v[114:117]
	v_mfma_f32_16x16x32_bf16 v[110:113], v[176:179], v[192:195], v[110:113]
	v_mfma_f32_16x16x32_bf16 v[98:101], v[168:171], v[208:211], v[98:101]
	v_mfma_f32_16x16x32_bf16 v[90:93], v[176:179], v[208:211], v[90:93]
	v_mfma_f32_16x16x32_bf16 v[78:81], v[168:171], v[216:219], v[78:81]
	v_mfma_f32_16x16x32_bf16 v[74:77], v[176:179], v[216:219], v[74:77]
	v_mfma_f32_16x16x32_bf16 v[130:133], v[172:175], v[188:191], v[130:133]
	v_mfma_f32_16x16x32_bf16 v[126:129], v[180:183], v[188:191], v[126:129]
	v_mfma_f32_16x16x32_bf16 v[114:117], v[172:175], v[196:199], v[114:117]
	v_mfma_f32_16x16x32_bf16 v[110:113], v[180:183], v[196:199], v[110:113]
	v_mfma_f32_16x16x32_bf16 v[98:101], v[172:175], v[212:215], v[98:101]
	v_mfma_f32_16x16x32_bf16 v[90:93], v[180:183], v[212:215], v[90:93]
	v_mfma_f32_16x16x32_bf16 v[78:81], v[172:175], v[220:223], v[78:81]
	v_mfma_f32_16x16x32_bf16 v[74:77], v[180:183], v[220:223], v[74:77]
	s_setprio 0
	s_barrier
; #define PG8_STAGE(bufoff, gbase, voff) do { _Pragma("unroll") for (int _i = 0; _i < 2; ++_i) \
;         __builtin_amdgcn_global_load_lds((const unsigned*)((const char*)(gbase) + (voff)[_i]), (PG8_LAS unsigned*)(lds + (bufoff) + ldsw + _i * 8192), 16, 0, 0); } while (0)
; #define PG8_LDA(dst, b, h) do { _Pragma("unroll") for (int m = 0; m < 4; ++m) _Pragma("unroll") for (int k = 0; k < 2; ++k) dst[m][k] = *(const PG8_LAS bf16x8*)(lds + PG8_SA(b, h) + aoff + m * 2048 + k * 1024); } while (0)
; #define PG8_MMA(ai, bj, At, Bt) do { __builtin_amdgcn_s_setprio(1); _Pragma("unroll") for (int m = 0; m < 4; ++m) _Pragma("unroll") for (int n = 0; n < 2; ++n) _Pragma("unroll") for (int k = 0; k < 2; ++k) \
;         acc[ai][bj][m][n] = __builtin_amdgcn_mfma_f32_16x16x32_bf16(Bt[n][k], At[m][k], acc[ai][bj][m][n], 0, 0, 0); __builtin_amdgcn_s_setprio(0); } while (0)
; #define PG8_WAIT_V(n) asm volatile("s_waitcnt vmcnt(" #n ")" ::: "memory")
; #define PG8_WAIT_L(n) asm volatile("s_waitcnt lgkmcnt(" #n ")" ::: "memory")
; #define PG8_BAR __builtin_amdgcn_s_barrier()
; #define PG8_SCHED __builtin_amdgcn_sched_barrier(0)
; template <class Epi, class Sched, bool ALIGN_EPI = false, bool SP2 = false>
; __device__ __forceinline__ void gemm_phase(PG8_LAS unsigned char* lds, const Gemm g, const Sched& S, const Epi& E) {
;     ...
;         for (int t = 0; t < nt; t += 2) {
;     ...
;             PG8_LDA(At, 1, 1); PG8_STAGE(PG8_SB(1, 0), b3, voffB); PG8_STAGE(PG8_SB(1, 1), b3 + hstep, voffB); PG8_STAGE(PG8_SA(1, 0), a3, voffA);
;             PG8_WAIT_V(8); PG8_WAIT_L(0); PG8_BAR; PG8_MMA(1, 0, At, B0); PG8_MMA(1, 1, At, B1); PG8_BAR; PG8_SCHED;
	s_add_i32 s24, s47, s31
	v_lshl_add_u64 v[200:201], v[200:201], 0, s[16:17]
	s_mov_b32 m0, s24
	ds_read_b128 v[184:187], v151 offset:49152
	ds_read_b128 v[188:191], v151 offset:50176
	ds_read_b128 v[192:195], v151 offset:51200
	ds_read_b128 v[196:199], v151 offset:52224
	ds_read_b128 v[208:211], v151 offset:53248
	ds_read_b128 v[212:215], v151 offset:54272
	ds_read_b128 v[216:219], v151 offset:55296
	ds_read_b128 v[220:223], v151 offset:56320
	global_load_lds_dwordx4 v[200:201], off
	s_add_i32 m0, s24, 0x2000
	s_add_u32 s22, s22, 0xb0080
	v_lshl_add_u64 v[200:201], v[204:205], 0, s[16:17]
	s_addc_u32 s23, s23, 0
	s_add_i32 s24, s48, s31
	global_load_lds_dwordx4 v[200:201], off
	v_lshl_add_u64 v[200:201], s[22:23], 0, v[12:13]
	s_mov_b32 m0, s24
	s_nop 0
	global_load_lds_dwordx4 v[200:201], off
	v_lshl_add_u64 v[200:201], s[22:23], 0, v[56:57]
	s_add_i32 m0, s24, 0x2000
	s_nop 0
	global_load_lds_dwordx4 v[200:201], off
	v_lshl_add_u64 v[200:201], v[224:225], 0, s[16:17]
	s_mov_b32 m0, s38
	s_nop 0
	global_load_lds_dwordx4 v[200:201], off
	v_lshl_add_u64 v[200:201], v[226:227], 0, s[16:17]
	s_mov_b32 m0, s39
	s_nop 0
	global_load_lds_dwordx4 v[200:201], off
	s_waitcnt vmcnt(8)
	s_waitcnt lgkmcnt(0)
	s_barrier
	s_setprio 1
	s_waitcnt lgkmcnt(0)
	v_mfma_f32_16x16x32_bf16 v[70:73], v[152:155], v[184:187], v[70:73]
	v_mfma_f32_16x16x32_bf16 v[66:69], v[160:163], v[184:187], v[66:69]
	v_mfma_f32_16x16x32_bf16 v[50:53], v[152:155], v[192:195], v[50:53]
	v_mfma_f32_16x16x32_bf16 v[46:49], v[160:163], v[192:195], v[46:49]
	v_mfma_f32_16x16x32_bf16 v[34:37], v[152:155], v[208:211], v[34:37]
	v_mfma_f32_16x16x32_bf16 v[30:33], v[160:163], v[208:211], v[30:33]
	v_mfma_f32_16x16x32_bf16 v[18:21], v[152:155], v[216:219], v[18:21]
	v_mfma_f32_16x16x32_bf16 v[14:17], v[160:163], v[216:219], v[14:17]
	v_mfma_f32_16x16x32_bf16 v[70:73], v[156:159], v[188:191], v[70:73]
	v_mfma_f32_16x16x32_bf16 v[66:69], v[164:167], v[188:191], v[66:69]
	v_mfma_f32_16x16x32_bf16 v[50:53], v[156:159], v[196:199], v[50:53]
	v_mfma_f32_16x16x32_bf16 v[46:49], v[164:167], v[196:199], v[46:49]
	v_mfma_f32_16x16x32_bf16 v[34:37], v[156:159], v[212:215], v[34:37]
	v_mfma_f32_16x16x32_bf16 v[30:33], v[164:167], v[212:215], v[30:33]
	v_mfma_f32_16x16x32_bf16 v[18:21], v[156:159], v[220:223], v[18:21]
	v_mfma_f32_16x16x32_bf16 v[14:17], v[164:167], v[220:223], v[14:17]
	s_setprio 0
	s_setprio 1
	v_mfma_f32_16x16x32_bf16 v[62:65], v[168:171], v[184:187], v[62:65]
	v_mfma_f32_16x16x32_bf16 v[58:61], v[176:179], v[184:187], v[58:61]
	v_mfma_f32_16x16x32_bf16 v[42:45], v[168:171], v[192:195], v[42:45]
	v_mfma_f32_16x16x32_bf16 v[38:41], v[176:179], v[192:195], v[38:41]
	v_mfma_f32_16x16x32_bf16 v[26:29], v[168:171], v[208:211], v[26:29]
	v_mfma_f32_16x16x32_bf16 v[22:25], v[176:179], v[208:211], v[22:25]
	v_mfma_f32_16x16x32_bf16 v[6:9], v[168:171], v[216:219], v[6:9]
	v_mfma_f32_16x16x32_bf16 v[2:5], v[176:179], v[216:219], v[2:5]
	v_mfma_f32_16x16x32_bf16 v[62:65], v[172:175], v[188:191], v[62:65]
	v_mfma_f32_16x16x32_bf16 v[58:61], v[180:183], v[188:191], v[58:61]
	v_mfma_f32_16x16x32_bf16 v[42:45], v[172:175], v[196:199], v[42:45]
	v_mfma_f32_16x16x32_bf16 v[38:41], v[180:183], v[196:199], v[38:41]
	v_mfma_f32_16x16x32_bf16 v[26:29], v[172:175], v[212:215], v[26:29]
	v_mfma_f32_16x16x32_bf16 v[22:25], v[180:183], v[212:215], v[22:25]
	v_mfma_f32_16x16x32_bf16 v[6:9], v[172:175], v[220:223], v[6:9]
	v_mfma_f32_16x16x32_bf16 v[2:5], v[180:183], v[220:223], v[2:5]
	s_setprio 0
	s_barrier
	s_add_i32 s46, s46, 2
	s_add_u32 s20, s20, 0x100
	s_addc_u32 s21, s21, 0
	s_cmp_gt_u32 s46, 41
	s_cbranch_scc0 .LBB0_1201
	s_branch .Lkexit4

; #define PG8_BAR __builtin_amdgcn_s_barrier()
; template <class Epi, class Sched, bool ALIGN_EPI = false, bool SP2 = false>
; __device__ __forceinline__ void gemm_phase(PG8_LAS unsigned char* lds, const Gemm g, const Sched& S, const Epi& E) {
;     ...
;         if (!has_next) break;
; #pragma unroll
;         for (int a = 0; a < 2; ++a)
; #pragma unroll
;             for (int b = 0; b < 2; ++b)
; #pragma unroll
;                 for (int m = 0; m < 4; ++m)
; #pragma unroll
;                     for (int n = 0; n < 2; ++n) acc[a][b][m][n] = (f32x4){0.f, 0.f, 0.f, 0.f};
;         cur = nxt; cA = nA; cB = nB; ++ui;
;         if constexpr (ALIGN_EPI) { if (wr == 1) PG8_BAR; }
.Lkexit4:
	s_add_u32 s20, s2, 0xffffff00
	s_addc_u32 s21, s3, -1
	s_and_b64 vcc, exec, s[4:5]
	s_cbranch_vccnz .LBB0_1188
	v_mov_b64_e32 v[2:3], 0
	s_mov_b32 s10, s43
	s_mov_b32 s28, s44
	s_mov_b64 s[12:13], s[18:19]
	s_mov_b32 s40, s45
	v_mov_b64_e32 v[4:5], 0
	v_mov_b64_e32 v[6:7], 0
	v_mov_b64_e32 v[8:9], 0
	v_mov_b64_e32 v[22:23], 0
	v_mov_b64_e32 v[24:25], 0
	v_mov_b64_e32 v[26:27], 0
	v_mov_b64_e32 v[28:29], 0
	v_mov_b64_e32 v[38:39], 0
	v_mov_b64_e32 v[40:41], 0
	v_mov_b64_e32 v[42:43], 0
	v_mov_b64_e32 v[44:45], 0
	v_mov_b64_e32 v[58:59], 0
	v_mov_b64_e32 v[60:61], 0
	v_mov_b64_e32 v[62:63], 0
	v_mov_b64_e32 v[64:65], 0
	v_mov_b64_e32 v[14:15], 0
	v_mov_b64_e32 v[16:17], 0
	v_mov_b64_e32 v[18:19], 0
	v_mov_b64_e32 v[20:21], 0
	v_mov_b64_e32 v[30:31], 0
	v_mov_b64_e32 v[32:33], 0
	v_mov_b64_e32 v[34:35], 0
	v_mov_b64_e32 v[36:37], 0
	v_mov_b64_e32 v[46:47], 0
	v_mov_b64_e32 v[48:49], 0
	v_mov_b64_e32 v[50:51], 0
	v_mov_b64_e32 v[52:53], 0
	v_mov_b64_e32 v[66:67], 0
	v_mov_b64_e32 v[68:69], 0
	v_mov_b64_e32 v[70:71], 0
	v_mov_b64_e32 v[72:73], 0
	v_mov_b64_e32 v[74:75], 0
	v_mov_b64_e32 v[76:77], 0
	v_mov_b64_e32 v[78:79], 0
	v_mov_b64_e32 v[80:81], 0
	v_mov_b64_e32 v[90:91], 0
	v_mov_b64_e32 v[92:93], 0
	v_mov_b64_e32 v[98:99], 0
	v_mov_b64_e32 v[100:101], 0
	v_mov_b64_e32 v[110:111], 0
	v_mov_b64_e32 v[112:113], 0
	v_mov_b64_e32 v[114:115], 0
	v_mov_b64_e32 v[116:117], 0
	v_mov_b64_e32 v[126:127], 0
	v_mov_b64_e32 v[128:129], 0
	v_mov_b64_e32 v[130:131], 0
	v_mov_b64_e32 v[132:133], 0
	v_mov_b64_e32 v[82:83], 0
	v_mov_b64_e32 v[84:85], 0
	v_mov_b64_e32 v[86:87], 0
	v_mov_b64_e32 v[88:89], 0
	v_mov_b64_e32 v[102:103], 0
	v_mov_b64_e32 v[104:105], 0
	v_mov_b64_e32 v[106:107], 0
	v_mov_b64_e32 v[108:109], 0
	v_mov_b64_e32 v[118:119], 0
	v_mov_b64_e32 v[120:121], 0
	v_mov_b64_e32 v[122:123], 0
	v_mov_b64_e32 v[124:125], 0
	v_mov_b64_e32 v[138:139], 0
	v_mov_b64_e32 v[140:141], 0
	v_mov_b64_e32 v[142:143], 0
	v_mov_b64_e32 v[144:145], 0
	s_andn2_b64 vcc, exec, s[0:1]
	s_cbranch_vccnz .LBB0_1189
